# adaLN GEMV: 4 W-row loads issued together with counted waits; row reductions via DPP/permlane-swap instead of ds_bpermute (bitwise same sums)
# speedup vs baseline: 1.0009x; 1.0009x over previous
; DI int tid_opaque() { int t = threadIdx.x; asm volatile("" : "+v"(t)); return t; }
; DI float row_rms_scale(const Row32& r) {
;     float s = 0.f;
; #pragma unroll
;     for (int i = 0; i < 8; ++i) s += (r.v[i].x * r.v[i].x + r.v[i].y * r.v[i].y) + (r.v[i].z * r.v[i].z + r.v[i].w * r.v[i].w);
;     s = wave_sum(s);
;     return 1.0f / sqrtf(s * (1.f / DM) + EPS);
; }
; DI void norm_mod_store(const Row32& x, float rs, const float* g, const float* shift, const float* scale, bf16_t* dst, int lane) {
;     Row32 gg, sh, sc, o; ld_row_f32(gg, g, lane); ld_row_f32(sh, shift, lane); ld_row_f32(sc, scale, lane);
; #pragma unroll
;     for (int i = 0; i < 8; ++i) o.v[i] = (x.v[i] * rs * gg.v[i]) * (1.f + sc.v[i]) + sh.v[i];
;     st_row_bf16(o, dst, lane);
; }
; DI void ew_h0(ArgsRef a) {
;     const int tid = tid_opaque(), lane = tid & 63, gw = blockIdx.x * 8 + (tid >> 6), NGW = gridDim.x * 8;
;     const float* MODS = (const float*)(a.ws + WS_MODS); bf16_t* H = (bf16_t*)(a.ws + WS_H);
;     auto xin = [&](int g) -> const float* { return g < MLAT ? a.in[I_X] + (size_t)g * DM : a.in[I_CTX] + (size_t)(g - MLAT) * DM; };
;     auto finish = [&](int g, Row32& x) {
;         const float rs = row_rms_scale(x);
;         const float* md = MODS + (size_t)row_mod_idx(g) * NMODS;
;         norm_mod_store(x, rs, a.in[I_GPREMIX], md + 0 * DM, md + 1 * DM, H + hpad_row(g) * DM, lane); };
.LBB0_23:
	s_or_b64 exec, exec, s[16:17]
	s_waitcnt vmcnt(6)
	v_mul_f32_e32 v64, v61, v61
	v_mul_f32_e32 v65, v63, v63
	v_fmac_f32_e32 v64, v60, v60
	v_fmac_f32_e32 v65, v62, v62
	v_add_f32_e32 v64, v64, v65
	v_mul_f32_e32 v65, v57, v57
	v_mul_f32_e32 v67, v59, v59
	v_fmac_f32_e32 v65, v56, v56
	v_fmac_f32_e32 v67, v58, v58
	v_add_f32_e32 v65, v65, v67
	v_add_f32_e32 v64, v64, v65
	s_waitcnt vmcnt(4)
	v_mul_f32_e32 v65, v53, v53
	v_mul_f32_e32 v67, v55, v55
	v_fmac_f32_e32 v65, v52, v52
	v_fmac_f32_e32 v67, v54, v54
	v_add_f32_e32 v65, v65, v67
	v_add_f32_e32 v64, v64, v65
	v_mul_f32_e32 v65, v49, v49
	v_mul_f32_e32 v67, v51, v51
	v_fmac_f32_e32 v65, v48, v48
	v_fmac_f32_e32 v67, v50, v50
	v_add_f32_e32 v65, v65, v67
	v_add_f32_e32 v64, v64, v65
	s_waitcnt vmcnt(3)
	v_mul_f32_e32 v65, v45, v45
	v_mul_f32_e32 v67, v47, v47
	v_fmac_f32_e32 v65, v44, v44
	v_fmac_f32_e32 v67, v46, v46
	v_add_f32_e32 v65, v65, v67
	v_add_f32_e32 v64, v64, v65
	s_waitcnt vmcnt(2)
	v_mul_f32_e32 v65, v41, v41
	v_mul_f32_e32 v67, v43, v43
	v_fmac_f32_e32 v65, v40, v40
	v_fmac_f32_e32 v67, v42, v42
	v_add_f32_e32 v65, v65, v67
	v_add_f32_e32 v64, v64, v65
	s_waitcnt vmcnt(1)
	v_mul_f32_e32 v65, v37, v37
	v_mul_f32_e32 v67, v39, v39
	v_fmac_f32_e32 v65, v36, v36
	v_fmac_f32_e32 v67, v38, v38
	v_add_f32_e32 v65, v65, v67
	v_add_f32_e32 v64, v64, v65
	s_waitcnt vmcnt(0)
	v_mul_f32_e32 v65, v33, v33
	v_mul_f32_e32 v67, v35, v35
	v_fmac_f32_e32 v65, v32, v32
	v_fmac_f32_e32 v67, v34, v34
	v_add_f32_e32 v65, v65, v67
	v_add_f32_e32 v64, v64, v65
	s_waitcnt lgkmcnt(0)
	s_nop 1
	v_add_f32_dpp v64, v64, v64 quad_perm:[1,0,3,2] row_mask:0xf bank_mask:0xf
	s_waitcnt lgkmcnt(0)
	s_nop 1
	v_add_f32_dpp v64, v64, v64 quad_perm:[2,3,0,1] row_mask:0xf bank_mask:0xf
	s_waitcnt lgkmcnt(0)
	s_nop 1
	v_add_f32_dpp v64, v64, v64 row_half_mirror row_mask:0xf bank_mask:0xf
	s_waitcnt lgkmcnt(0)
	s_nop 1
	v_add_f32_dpp v64, v64, v64 row_mirror row_mask:0xf bank_mask:0xf
	s_waitcnt lgkmcnt(0)
	v_mov_b32_e32 v65, v64
	s_nop 1
	v_permlane16_swap_b32_e32 v64, v65
	v_add_f32_e32 v67, v64, v65
	ds_bpermute_b32 v68, v164, v67
	s_and_saveexec_b64 s[16:17], s[8:9]
	s_xor_b64 s[8:9], exec, s[16:17]
	v_lshrrev_b32_e32 v64, 8, v66
	v_mul_hi_u32_u24_e32 v65, 0x102, v64
	v_mul_u32_u24_e32 v64, 0x102, v64
	s_or_saveexec_b64 s[8:9], s[8:9]
	v_mov_b32_e32 v66, 0x8011
	v_mov_b32_e32 v69, 0xff
	s_xor_b64 exec, exec, s[8:9]
	v_ashrrev_i32_e32 v64, 12, v165
	v_mul_hi_i32_i24_e32 v65, 0x1002, v64
	v_mul_i32_i24_e32 v64, 0x1002, v64
	v_mov_b32_e32 v66, 1
	v_mov_b32_e32 v69, 0xfff
	s_or_b64 exec, exec, s[8:9]
	s_waitcnt lgkmcnt(0)
	v_add_f32_e32 v67, v67, v68
	v_fmamk_f32 v67, v67, 0x3a000000, v189
	v_cmp_gt_f32_e32 vcc, s71, v67
	v_mul_f32_e32 v68, 0x4f800000, v67
	v_min_i32_e32 v70, 0x8000, v165
	v_cndmask_b32_e32 v67, v67, v68, vcc
	v_sqrt_f32_e32 v68, v67
	v_ashrrev_i32_e32 v70, 12, v70
	v_mul_hi_i32_i24_e32 v71, 0xc000, v70
	v_mul_i32_i24_e32 v70, 0xc000, v70
	v_lshl_add_u64 v[88:89], s[82:83], 0, v[70:71]
	v_add_u32_e32 v70, -1, v68
	v_fma_f32 v71, -v70, v68, v67
	v_cmp_ge_f32_e64 s[8:9], 0, v71
	v_add_u32_e32 v71, 1, v68
	v_mov_b32_e32 v153, v185
	v_cndmask_b32_e64 v70, v68, v70, s[8:9]
	v_fma_f32 v68, -v71, v68, v67
	v_cmp_lt_f32_e64 s[8:9], 0, v68
	v_lshl_add_u64 v[180:181], v[88:89], 0, v[152:153]
	v_lshl_add_u64 v[168:169], v[180:181], 0, s[64:65]
	v_cndmask_b32_e64 v68, v70, v71, s[8:9]
	v_mul_f32_e32 v70, 0x37800000, v68
	v_cndmask_b32_e32 v68, v68, v70, vcc
	v_cmp_class_f32_e32 vcc, v67, v227
	s_nop 1
	v_cndmask_b32_e32 v67, v68, v67, vcc
	v_div_scale_f32 v68, s[8:9], v67, v67, 1.0
	v_rcp_f32_e32 v70, v68
	s_mov_b64 s[8:9], 0x1000
	v_lshl_add_u64 v[88:89], v[180:181], 0, s[8:9]
	s_movk_i32 s8, 0x2000
	v_fma_f32 v71, -v68, v70, 1.0
	v_fmac_f32_e32 v70, v71, v70
	v_div_scale_f32 v71, vcc, 1.0, v67, 1.0
	v_mul_f32_e32 v72, v71, v70
	v_fma_f32 v73, -v68, v72, v71
	v_fmac_f32_e32 v72, v73, v70
	v_fma_f32 v68, -v68, v72, v71
	v_div_fmas_f32 v68, v68, v70, v72
	v_add_co_u32_e32 v90, vcc, s70, v180
	v_div_fixup_f32 v158, v68, v67, 1.0
	v_and_b32_e32 v67, v69, v165
	v_addc_co_u32_e32 v91, vcc, 0, v181, vcc
	v_add_u32_e32 v184, v67, v66
	v_add_co_u32_e32 v128, vcc, s8, v180
	v_lshl_add_u64 v[64:65], v[64:65], 0, v[184:185]
	s_nop 0
	v_addc_co_u32_e32 v129, vcc, 0, v181, vcc
	v_lshlrev_b64 v[156:157], 12, v[64:65]
	global_load_dwordx4 v[64:67], v[142:143], off offset:16
	global_load_dwordx4 v[112:115], v[142:143], off
	global_load_dwordx4 v[84:87], v[142:143], off offset:2064
	global_load_dwordx4 v[92:95], v[142:143], off offset:2048
	global_load_dwordx4 v[76:79], v[144:145], off offset:16
	global_load_dwordx4 v[80:83], v[144:145], off
	global_load_dwordx4 v[68:71], v[146:147], off offset:16
	global_load_dwordx4 v[72:75], v[146:147], off
	global_load_dwordx4 v[120:123], v[180:181], off offset:16
	global_load_dwordx4 v[124:127], v[180:181], off
	global_load_dwordx4 v[100:103], v[180:181], off offset:2064
	global_load_dwordx4 v[108:111], v[180:181], off offset:2048
	global_load_dwordx4 v[116:119], v[128:129], off offset:-4096
	global_load_dwordx4 v[104:107], v[88:89], off offset:16
	v_lshl_add_u64 v[88:89], v[180:181], 0, s[22:23]
	s_mov_b64 s[8:9], 0x3000
	global_load_dwordx4 v[96:99], v[90:91], off offset:2048
	s_nop 0
	global_load_dwordx4 v[88:91], v[88:89], off offset:16
	s_nop 0
	global_load_dwordx4 v[132:135], v[128:129], off
	global_load_dwordx4 v[136:139], v[168:169], off offset:16
	s_nop 0
	global_load_dwordx4 v[128:131], v[168:169], off offset:2064
	s_nop 0
	global_load_dwordx4 v[168:171], v[168:169], off offset:2048
	v_lshl_add_u64 v[176:177], v[180:181], 0, s[8:9]
	s_movk_i32 s8, 0x3000
	v_add_co_u32_e32 v182, vcc, s8, v180
	s_mov_b64 s[8:9], 0x3800
	s_nop 0
	v_addc_co_u32_e32 v183, vcc, 0, v181, vcc
	global_load_dwordx4 v[172:175], v[182:183], off
	s_nop 0
	global_load_dwordx4 v[176:179], v[176:177], off offset:16
	v_lshl_add_u64 v[194:195], v[180:181], 0, s[8:9]
	global_load_dwordx4 v[180:183], v[182:183], off offset:2048
	s_nop 0
	global_load_dwordx4 v[194:197], v[194:195], off offset:16
	v_pk_mul_f32 v[58:59], v[58:59], v[158:159] op_sel_hi:[1,0]
	v_pk_mul_f32 v[56:57], v[56:57], v[158:159] op_sel_hi:[1,0]
	v_pk_mul_f32 v[54:55], v[54:55], v[158:159] op_sel_hi:[1,0]
	v_pk_mul_f32 v[52:53], v[52:53], v[158:159] op_sel_hi:[1,0]
	v_pk_mul_f32 v[50:51], v[50:51], v[158:159] op_sel_hi:[1,0]
	v_pk_mul_f32 v[48:49], v[48:49], v[158:159] op_sel_hi:[1,0]
	v_pk_mul_f32 v[46:47], v[46:47], v[158:159] op_sel_hi:[1,0]
	v_pk_mul_f32 v[44:45], v[44:45], v[158:159] op_sel_hi:[1,0]
	v_pk_mul_f32 v[42:43], v[42:43], v[158:159] op_sel_hi:[1,0]
	v_pk_mul_f32 v[40:41], v[40:41], v[158:159] op_sel_hi:[1,0]
	v_pk_mul_f32 v[62:63], v[62:63], v[158:159] op_sel_hi:[1,0]
	v_pk_mul_f32 v[60:61], v[60:61], v[158:159] op_sel_hi:[1,0]
	v_pk_mul_f32 v[38:39], v[38:39], v[158:159] op_sel_hi:[1,0]
	v_pk_mul_f32 v[36:37], v[36:37], v[158:159] op_sel_hi:[1,0]
	v_pk_mul_f32 v[34:35], v[34:35], v[158:159] op_sel_hi:[1,0]
	v_pk_mul_f32 v[32:33], v[32:33], v[158:159] op_sel_hi:[1,0]
	s_waitcnt vmcnt(23)
; DI int tid_opaque() { int t = threadIdx.x; asm volatile("" : "+v"(t)); return t; }
; DI void norm_mod_store(const Row32& x, float rs, const float* g, const float* shift, const float* scale, bf16_t* dst, int lane) {
;     Row32 gg, sh, sc, o; ld_row_f32(gg, g, lane); ld_row_f32(sh, shift, lane); ld_row_f32(sc, scale, lane);
; #pragma unroll
;     for (int i = 0; i < 8; ++i) o.v[i] = (x.v[i] * rs * gg.v[i]) * (1.f + sc.v[i]) + sh.v[i];
;     st_row_bf16(o, dst, lane);
; }
; DI void ew_h0(ArgsRef a) {
;     const int tid = tid_opaque(), lane = tid & 63, gw = blockIdx.x * 8 + (tid >> 6), NGW = gridDim.x * 8;
;     const float* MODS = (const float*)(a.ws + WS_MODS); bf16_t* H = (bf16_t*)(a.ws + WS_H);
;     auto xin = [&](int g) -> const float* { return g < MLAT ? a.in[I_X] + (size_t)g * DM : a.in[I_CTX] + (size_t)(g - MLAT) * DM; };
;     auto finish = [&](int g, Row32& x) {
;         const float rs = row_rms_scale(x);
;         const float* md = MODS + (size_t)row_mod_idx(g) * NMODS;
;         norm_mod_store(x, rs, a.in[I_GPREMIX], md + 0 * DM, md + 1 * DM, H + hpad_row(g) * DM, lane); };
;     for (int g = gw; g < MALL; g += 2 * NGW) {
;         const int g2 = g + NGW; const bool has2 = g2 < MALL;
;         Row32 xA, xB;
;         ld_row_f32(xA, xin(g), lane);
;         if (has2) ld_row_f32(xB, xin(g2), lane);
;         finish(g, xA);
;         if (has2) finish(g2, xB);
	v_pk_mul_f32 v[56:57], v[56:57], v[64:65]
	v_pk_mul_f32 v[58:59], v[58:59], v[66:67]
	s_waitcnt vmcnt(21)
	v_pk_mul_f32 v[48:49], v[48:49], v[84:85]
	s_waitcnt vmcnt(20)
	v_pk_mul_f32 v[52:53], v[52:53], v[92:93]
	v_pk_mul_f32 v[54:55], v[54:55], v[94:95]
	v_pk_mul_f32 v[50:51], v[50:51], v[86:87]
	s_waitcnt vmcnt(18)
	v_pk_mul_f32 v[44:45], v[44:45], v[80:81]
	v_pk_mul_f32 v[46:47], v[46:47], v[82:83]
	v_pk_mul_f32 v[40:41], v[40:41], v[76:77]
	v_pk_mul_f32 v[42:43], v[42:43], v[78:79]
	v_pk_mul_f32 v[60:61], v[60:61], v[112:113]
	s_waitcnt vmcnt(6)
	v_pk_add_f32 v[64:65], v[138:139], 1.0 op_sel_hi:[1,0]
	v_pk_add_f32 v[66:67], v[136:137], 1.0 op_sel_hi:[1,0]
	v_pk_fma_f32 v[58:59], v[58:59], v[64:65], v[122:123]
	v_pk_fma_f32 v[56:57], v[56:57], v[66:67], v[120:121]
	s_waitcnt vmcnt(4)
	v_pk_add_f32 v[64:65], v[170:171], 1.0 op_sel_hi:[1,0]
	v_pk_add_f32 v[66:67], v[168:169], 1.0 op_sel_hi:[1,0]
	v_pk_fma_f32 v[54:55], v[54:55], v[64:65], v[110:111]
	v_pk_fma_f32 v[52:53], v[52:53], v[66:67], v[108:109]
	v_pk_add_f32 v[64:65], v[130:131], 1.0 op_sel_hi:[1,0]
	v_pk_add_f32 v[66:67], v[128:129], 1.0 op_sel_hi:[1,0]
	v_pk_fma_f32 v[50:51], v[50:51], v[64:65], v[102:103]
	v_pk_fma_f32 v[48:49], v[48:49], v[66:67], v[100:101]
	s_waitcnt vmcnt(3)
	v_pk_add_f32 v[64:65], v[174:175], 1.0 op_sel_hi:[1,0]
	v_pk_add_f32 v[66:67], v[172:173], 1.0 op_sel_hi:[1,0]
	v_pk_fma_f32 v[46:47], v[46:47], v[64:65], v[118:119]
	v_pk_fma_f32 v[44:45], v[44:45], v[66:67], v[116:117]
	s_waitcnt vmcnt(2)
	v_pk_add_f32 v[64:65], v[178:179], 1.0 op_sel_hi:[1,0]
	v_pk_add_f32 v[66:67], v[176:177], 1.0 op_sel_hi:[1,0]
	v_pk_mul_f32 v[62:63], v[62:63], v[114:115]
	v_pk_add_f32 v[112:113], v[134:135], 1.0 op_sel_hi:[1,0]
	v_pk_add_f32 v[114:115], v[132:133], 1.0 op_sel_hi:[1,0]
	v_pk_fma_f32 v[42:43], v[42:43], v[64:65], v[106:107]
	v_pk_fma_f32 v[40:41], v[40:41], v[66:67], v[104:105]
	v_pk_mul_f32 v[36:37], v[36:37], v[72:73]
	v_pk_mul_f32 v[38:39], v[38:39], v[74:75]
	s_waitcnt vmcnt(1)
	v_pk_add_f32 v[64:65], v[182:183], 1.0 op_sel_hi:[1,0]
	v_pk_add_f32 v[66:67], v[180:181], 1.0 op_sel_hi:[1,0]
	v_pk_fma_f32 v[62:63], v[62:63], v[112:113], v[126:127]
	v_pk_fma_f32 v[60:61], v[60:61], v[114:115], v[124:125]
	v_pk_fma_f32 v[38:39], v[38:39], v[64:65], v[98:99]
	v_pk_fma_f32 v[36:37], v[36:37], v[66:67], v[96:97]
	v_pk_mul_f32 v[32:33], v[32:33], v[68:69]
	v_pk_mul_f32 v[34:35], v[34:35], v[70:71]
	s_waitcnt vmcnt(0)
	v_pk_add_f32 v[64:65], v[196:197], 1.0 op_sel_hi:[1,0]
	v_pk_add_f32 v[66:67], v[194:195], 1.0 op_sel_hi:[1,0]
	v_pk_fma_f32 v[64:65], v[34:35], v[64:65], v[90:91]
	v_pk_fma_f32 v[66:67], v[32:33], v[66:67], v[88:89]
	v_lshl_add_u64 v[68:69], v[148:149], 0, v[156:157]
	v_cvt_pk_bf16_f32 v32, v60, v61
	v_cvt_pk_bf16_f32 v33, v62, v63
	v_cvt_pk_bf16_f32 v34, v56, v57
	v_cvt_pk_bf16_f32 v35, v58, v59
	global_store_dwordx4 v[68:69], v[32:35], off
	s_nop 1
	v_cvt_pk_bf16_f32 v32, v52, v53
	v_cvt_pk_bf16_f32 v33, v54, v55
	v_cvt_pk_bf16_f32 v34, v48, v49
	v_cvt_pk_bf16_f32 v35, v50, v51
	global_store_dwordx4 v[68:69], v[32:35], off offset:1024
	s_nop 1
	v_cvt_pk_bf16_f32 v32, v44, v45
	v_cvt_pk_bf16_f32 v33, v46, v47
	v_cvt_pk_bf16_f32 v34, v40, v41
	v_cvt_pk_bf16_f32 v35, v42, v43
	global_store_dwordx4 v[68:69], v[32:35], off offset:2048
	s_nop 1
	v_cvt_pk_bf16_f32 v32, v36, v37
	v_cvt_pk_bf16_f32 v33, v38, v39
	v_cvt_pk_bf16_f32 v34, v66, v67
	v_cvt_pk_bf16_f32 v35, v64, v65
	global_store_dwordx4 v[68:69], v[32:35], off offset:3072
	s_and_saveexec_b64 s[8:9], s[6:7]
	s_cbranch_execz .LBB0_20
	v_mul_f32_e32 v32, v1, v1
	v_mul_f32_e32 v33, v3, v3
	v_fmac_f32_e32 v32, v0, v0
	v_fmac_f32_e32 v33, v2, v2
	v_add_f32_e32 v32, v32, v33
	v_mul_f32_e32 v33, v5, v5
	v_mul_f32_e32 v34, v7, v7
	v_fmac_f32_e32 v33, v4, v4
	v_fmac_f32_e32 v34, v6, v6
	v_add_f32_e32 v33, v33, v34
	v_add_f32_e32 v32, v33, v32
	v_mul_f32_e32 v33, v9, v9
	v_mul_f32_e32 v34, v11, v11
	v_fmac_f32_e32 v33, v8, v8
	v_fmac_f32_e32 v34, v10, v10
	v_add_f32_e32 v33, v33, v34
	v_add_f32_e32 v32, v33, v32
	v_mul_f32_e32 v33, v13, v13
	v_mul_f32_e32 v34, v15, v15
	v_fmac_f32_e32 v33, v12, v12
	v_fmac_f32_e32 v34, v14, v14
	v_add_f32_e32 v33, v33, v34
	v_add_f32_e32 v32, v33, v32
	v_mul_f32_e32 v33, v17, v17
	v_mul_f32_e32 v34, v19, v19
	v_fmac_f32_e32 v33, v16, v16
	v_fmac_f32_e32 v34, v18, v18
	v_add_f32_e32 v33, v33, v34
	v_add_f32_e32 v32, v33, v32
	v_mul_f32_e32 v33, v21, v21
	v_mul_f32_e32 v34, v23, v23
	v_fmac_f32_e32 v33, v20, v20
	v_fmac_f32_e32 v34, v22, v22
	v_add_f32_e32 v33, v33, v34
	v_add_f32_e32 v32, v33, v32
	v_mul_f32_e32 v33, v25, v25
	v_mul_f32_e32 v34, v27, v27
	v_fmac_f32_e32 v33, v24, v24
	v_fmac_f32_e32 v34, v26, v26
	v_add_f32_e32 v33, v33, v34
	v_add_f32_e32 v32, v33, v32
	v_mul_f32_e32 v33, v29, v29
	v_mul_f32_e32 v34, v31, v31
	v_fmac_f32_e32 v33, v28, v28
	v_fmac_f32_e32 v34, v30, v30
	v_add_f32_e32 v33, v33, v34
	v_add_f32_e32 v32, v33, v32
	v_cmp_lt_i32_e32 vcc, s63, v166
	s_waitcnt lgkmcnt(0)
	s_nop 1
	v_add_f32_dpp v32, v32, v32 quad_perm:[1,0,3,2] row_mask:0xf bank_mask:0xf
	s_waitcnt lgkmcnt(0)
	s_nop 1
	v_add_f32_dpp v32, v32, v32 quad_perm:[2,3,0,1] row_mask:0xf bank_mask:0xf
	s_waitcnt lgkmcnt(0)
	s_nop 1
	v_add_f32_dpp v32, v32, v32 row_half_mirror row_mask:0xf bank_mask:0xf
	s_waitcnt lgkmcnt(0)
	s_nop 1
	v_add_f32_dpp v32, v32, v32 row_mirror row_mask:0xf bank_mask:0xf
	s_waitcnt lgkmcnt(0)
	v_mov_b32_e32 v33, v32
	s_nop 1
	v_permlane16_swap_b32_e32 v32, v33
	v_add_f32_e32 v35, v32, v33
	ds_bpermute_b32 v36, v164, v35
	s_and_saveexec_b64 s[6:7], vcc
	s_xor_b64 s[6:7], exec, s[6:7]
	v_add_u32_e32 v32, 0xffff8000, v166
	v_lshrrev_b32_e32 v32, 8, v32
	v_mul_hi_u32_u24_e32 v33, 0x102, v32
	v_mul_u32_u24_e32 v32, 0x102, v32
	s_or_saveexec_b64 s[6:7], s[6:7]
	v_mov_b32_e32 v34, 0x8011
	v_mov_b32_e32 v37, 0xff
	s_xor_b64 exec, exec, s[6:7]
	s_cbranch_execz .LBB0_19
	v_ashrrev_i32_e32 v32, 12, v166
	v_mul_hi_i32_i24_e32 v33, 0x1002, v32
	v_mul_i32_i24_e32 v32, 0x1002, v32
	v_mov_b32_e32 v34, 1
	v_mov_b32_e32 v37, 0xfff
	s_branch .LBB0_19

; DI float row_rms_scale(const Row32& r) {
;     float s = 0.f;
; #pragma unroll
;     for (int i = 0; i < 8; ++i) s += (r.v[i].x * r.v[i].x + r.v[i].y * r.v[i].y) + (r.v[i].z * r.v[i].z + r.v[i].w * r.v[i].w);
;     s = wave_sum(s);
;     return 1.0f / sqrtf(s * (1.f / DM) + EPS);
; DI void ew1(ArgsRef a, int l) {
;     ...
;         const float r1 = row_rms_scale(mx);
;         ld_row_f32(t, a.in[I_GPOSTMIX] + l * DM, lane);
; #pragma unroll
;         for (int i = 0; i < 8; ++i) mx.v[i] = mx.v[i] * r1 * t.v[i];
;         ld_row_f32(t, md + 2 * DM, lane);
.LBB0_172:
	s_or_b64 exec, exec, s[0:1]
	v_mov_b32_e32 v130, s97
	v_mov_b32_e32 v131, s17
	v_cndmask_b32_e64 v131, v130, v131, s[10:11]
	v_mov_b32_e32 v130, s96
	s_waitcnt vmcnt(0)
	v_mov_b32_e32 v132, s16
	v_mov_b32_e32 v134, v101
	v_mov_b32_e32 v135, v97
	v_cndmask_b32_e64 v130, v130, v132, s[10:11]
	v_mov_b32_e32 v132, v100
	v_mov_b32_e32 v133, v96
	v_pk_mul_f32 v[134:135], v[134:135], v[134:135]
	v_mov_b32_e32 v136, v103
	v_mov_b32_e32 v137, v99
	v_pk_fma_f32 v[132:133], v[132:133], v[132:133], v[134:135]
	v_mov_b32_e32 v134, v102
	v_mov_b32_e32 v135, v98
	v_pk_mul_f32 v[136:137], v[136:137], v[136:137]
	v_lshl_add_u64 v[130:131], v[130:131], 0, v[128:129]
	v_pk_fma_f32 v[134:135], v[134:135], v[134:135], v[136:137]
	v_pk_mul_f32 v[136:137], v[104:105], v[104:105]
	v_pk_add_f32 v[132:133], v[132:133], v[134:135]
	v_pk_mul_f32 v[134:135], v[106:107], v[106:107]
	v_pk_add_f32 v[132:133], v[132:133], v[132:133] op_sel_hi:[0,1]
	v_pk_mov_b32 v[138:139], v[136:137], v[134:135] op_sel:[1,0]
	v_mov_b32_e32 v137, v135
	v_mul_f32_e32 v132, v108, v108
	v_pk_add_f32 v[134:135], v[138:139], v[136:137]
	v_pk_fma_f32 v[136:137], v[108:109], v[108:109], v[132:133] op_sel_hi:[1,1,0]
	v_mul_f32_e32 v132, v110, v110
	v_pk_add_f32 v[134:135], v[134:135], v[134:135] op_sel_hi:[0,1]
	v_pk_fma_f32 v[138:139], v[110:111], v[110:111], v[132:133] op_sel_hi:[1,1,0]
	v_mul_f32_e32 v136, v112, v112
	v_mul_f32_e32 v138, v113, v113
	v_mul_f32_e32 v134, v114, v114
	v_mul_f32_e32 v132, v115, v115
	v_pk_add_f32 v[136:137], v[136:137], v[138:139]
	v_pk_add_f32 v[132:133], v[134:135], v[132:133]
	v_pk_mul_f32 v[134:135], v[118:119], v[118:119]
	v_pk_add_f32 v[132:133], v[136:137], v[132:133]
	v_pk_mul_f32 v[136:137], v[116:117], v[116:117]
	v_pk_add_f32 v[132:133], v[132:133], v[132:133] op_sel_hi:[0,1]
	v_pk_mov_b32 v[138:139], v[136:137], v[134:135] op_sel:[1,0]
	v_mov_b32_e32 v137, v135
	v_mul_f32_e32 v132, v120, v120
	v_pk_add_f32 v[134:135], v[138:139], v[136:137]
	v_pk_fma_f32 v[136:137], v[120:121], v[120:121], v[132:133] op_sel_hi:[1,1,0]
	v_mul_f32_e32 v132, v122, v122
	v_pk_add_f32 v[134:135], v[134:135], v[134:135] op_sel_hi:[0,1]
	v_pk_fma_f32 v[138:139], v[122:123], v[122:123], v[132:133] op_sel_hi:[1,1,0]
	v_mul_f32_e32 v136, v124, v124
	v_mul_f32_e32 v138, v125, v125
	v_mul_f32_e32 v134, v126, v126
	v_mul_f32_e32 v132, v127, v127
	v_pk_add_f32 v[136:137], v[136:137], v[138:139]
	v_pk_add_f32 v[132:133], v[134:135], v[132:133]
	v_min_i32_e32 v128, 0x8000, v152
	v_pk_add_f32 v[132:133], v[136:137], v[132:133]
	v_ashrrev_i32_e32 v128, 12, v128
	v_add_f32_e32 v132, v132, v133
	v_mul_hi_i32_i24_e32 v129, 0xc000, v128
	v_mul_i32_i24_e32 v128, 0xc000, v128
	v_mov_b32_e32 v181, v185
	s_waitcnt lgkmcnt(0)
	s_nop 1
	v_add_f32_dpp v132, v132, v132 quad_perm:[1,0,3,2] row_mask:0xf bank_mask:0xf
	s_waitcnt lgkmcnt(0)
	s_nop 1
	v_add_f32_dpp v132, v132, v132 quad_perm:[2,3,0,1] row_mask:0xf bank_mask:0xf
	s_waitcnt lgkmcnt(0)
	s_nop 1
	v_add_f32_dpp v132, v132, v132 row_half_mirror row_mask:0xf bank_mask:0xf
	s_waitcnt lgkmcnt(0)
	s_nop 1
	v_add_f32_dpp v132, v132, v132 row_mirror row_mask:0xf bank_mask:0xf
	s_waitcnt lgkmcnt(0)
	v_mov_b32_e32 v133, v132
	s_nop 1
	v_permlane16_swap_b32_e32 v132, v133
	v_add_f32_e32 v132, v132, v133
	s_waitcnt lgkmcnt(0)
	v_mov_b32_e32 v133, v132
	s_nop 1
	v_permlane32_swap_b32_e32 v132, v133
	v_add_f32_e32 v132, v132, v133
	v_fmamk_f32 v132, v132, 0x3a000000, v189
	v_cmp_gt_f32_e32 vcc, s71, v132
	v_mul_f32_e32 v133, 0x4f800000, v132
	s_nop 0
	v_cndmask_b32_e32 v132, v132, v133, vcc
	v_sqrt_f32_e32 v133, v132
	s_nop 0
	v_add_u32_e32 v134, -1, v133
	v_fma_f32 v135, -v134, v133, v132
	v_cmp_ge_f32_e64 s[10:11], 0, v135
	v_add_u32_e32 v135, 1, v133
	s_nop 0
	v_cndmask_b32_e64 v134, v133, v134, s[10:11]
	v_fma_f32 v133, -v135, v133, v132
	v_cmp_lt_f32_e64 s[10:11], 0, v133
	s_nop 1
	v_cndmask_b32_e64 v133, v134, v135, s[10:11]
	v_mul_f32_e32 v134, 0x37800000, v133
	v_cndmask_b32_e32 v133, v133, v134, vcc
	v_cmp_class_f32_e32 vcc, v132, v227
	s_nop 1
	v_cndmask_b32_e32 v132, v133, v132, vcc
	v_div_scale_f32 v133, s[0:1], v132, v132, 1.0
	v_rcp_f32_e32 v134, v133
	v_readlane_b32 s0, v254, 34
	v_readlane_b32 s1, v254, 35
	v_fma_f32 v135, -v133, v134, 1.0
	v_fmac_f32_e32 v134, v135, v134
	v_div_scale_f32 v135, vcc, 1.0, v132, 1.0
	v_mul_f32_e32 v136, v135, v134
	v_fma_f32 v137, -v133, v136, v135
	v_fmac_f32_e32 v136, v137, v134
	v_fma_f32 v133, -v133, v136, v135
	v_div_fmas_f32 v133, v133, v134, v136
	v_div_fixup_f32 v220, v133, v132, 1.0
	global_load_dwordx4 v[132:135], v[160:161], off offset:16
	global_load_dwordx4 v[136:139], v[160:161], off
	global_load_dwordx4 v[140:143], v[160:161], off offset:2064
	global_load_dwordx4 v[144:147], v[160:161], off offset:2048
	global_load_dwordx4 v[204:207], v[162:163], off offset:16
	global_load_dwordx4 v[208:211], v[162:163], off
	global_load_dwordx4 v[212:215], v[164:165], off offset:16
	global_load_dwordx4 v[216:219], v[164:165], off
	v_pk_mul_f32 v[98:99], v[98:99], v[220:221] op_sel_hi:[1,0]
	v_pk_mul_f32 v[96:97], v[96:97], v[220:221] op_sel_hi:[1,0]
	v_lshl_add_u64 v[128:129], s[0:1], 0, v[128:129]
	s_mov_b64 s[0:1], 0x4000
	s_waitcnt vmcnt(6)
	v_pk_mul_f32 v[202:203], v[138:139], v[98:99]
	v_pk_mul_f32 v[98:99], v[100:101], v[220:221] op_sel_hi:[1,0]
	v_pk_mul_f32 v[198:199], v[136:137], v[96:97]
	v_pk_mul_f32 v[96:97], v[102:103], v[220:221] op_sel_hi:[1,0]
	v_pk_mul_f32 v[194:195], v[132:133], v[98:99]
	v_pk_mul_f32 v[98:99], v[104:105], v[220:221] op_sel_hi:[1,0]
	v_pk_mul_f32 v[200:201], v[134:135], v[96:97]
	v_pk_mul_f32 v[96:97], v[106:107], v[220:221] op_sel_hi:[1,0]
	s_waitcnt vmcnt(4)
; DI void ew1(ArgsRef a, int l) {
;     ...
;         ld_row_f32(t, a.in[I_GPOSTMIX] + l * DM, lane);
; #pragma unroll
;         for (int i = 0; i < 8; ++i) mx.v[i] = mx.v[i] * r1 * t.v[i];
;         ld_row_f32(t, md + 2 * DM, lane);
; #pragma unroll
;         for (int i = 0; i < 8; ++i) x.v[i] = x.v[i] + t.v[i] * mx.v[i];
;         st_row_bf16(x, (bf16_t*)xo, lane);
;         const float r2 = row_rms_scale(x);
	v_pk_mul_f32 v[150:151], v[144:145], v[98:99]
	v_pk_mul_f32 v[98:99], v[108:109], v[220:221] op_sel_hi:[1,0]
	v_pk_mul_f32 v[196:197], v[146:147], v[96:97]
	v_pk_mul_f32 v[96:97], v[110:111], v[220:221] op_sel_hi:[1,0]
	v_pk_mul_f32 v[146:147], v[140:141], v[98:99]
	v_pk_mul_f32 v[98:99], v[112:113], v[220:221] op_sel_hi:[1,0]
	v_pk_mul_f32 v[182:183], v[142:143], v[96:97]
	s_waitcnt vmcnt(2)
	v_pk_mul_f32 v[142:143], v[208:209], v[98:99]
	v_pk_mul_f32 v[98:99], v[116:117], v[220:221] op_sel_hi:[1,0]
	v_pk_mul_f32 v[96:97], v[114:115], v[220:221] op_sel_hi:[1,0]
	v_pk_mul_f32 v[138:139], v[204:205], v[98:99]
	v_pk_mul_f32 v[98:99], v[120:121], v[220:221] op_sel_hi:[1,0]
	v_lshl_add_u64 v[120:121], v[128:129], 0, v[184:185]
	v_pk_mul_f32 v[148:149], v[210:211], v[96:97]
	v_pk_mul_f32 v[96:97], v[118:119], v[220:221] op_sel_hi:[1,0]
	v_lshl_add_u64 v[108:109], v[120:121], 0, s[0:1]
	s_movk_i32 s0, 0x5000
	v_pk_mul_f32 v[144:145], v[206:207], v[96:97]
	v_pk_mul_f32 v[96:97], v[122:123], v[220:221] op_sel_hi:[1,0]
	v_add_co_u32_e32 v122, vcc, s0, v120
	s_waitcnt vmcnt(0)
	v_pk_mul_f32 v[134:135], v[216:217], v[98:99]
	v_pk_mul_f32 v[140:141], v[218:219], v[96:97]
	v_pk_mul_f32 v[96:97], v[126:127], v[220:221] op_sel_hi:[1,0]
	v_pk_mul_f32 v[98:99], v[124:125], v[220:221] op_sel_hi:[1,0]
	v_addc_co_u32_e32 v123, vcc, 0, v121, vcc
	s_mov_b64 s[0:1], 0x5000
	v_pk_mul_f32 v[132:133], v[212:213], v[98:99]
	v_pk_mul_f32 v[136:137], v[214:215], v[96:97]
	global_load_dwordx4 v[104:107], v[122:123], off offset:-4096
	global_load_dwordx4 v[100:103], v[108:109], off offset:16
	global_load_dwordx4 v[96:99], v[108:109], off offset:2064
	global_load_dwordx4 v[112:115], v[108:109], off offset:2048
	v_lshl_add_u64 v[108:109], v[120:121], 0, s[0:1]
	s_mov_b64 s[0:1], 0x5800
	global_load_dwordx4 v[116:119], v[122:123], off
	s_nop 0
	global_load_dwordx4 v[108:111], v[108:109], off offset:16
	v_lshl_add_u64 v[120:121], v[120:121], 0, s[0:1]
	global_load_dwordx4 v[124:127], v[122:123], off offset:2048
	s_nop 0
	global_load_dwordx4 v[120:123], v[120:121], off offset:16
	s_waitcnt vmcnt(7)
	v_pk_fma_f32 v[220:221], v[106:107], v[202:203], v[70:71]
	v_pk_fma_f32 v[222:223], v[104:105], v[198:199], v[68:69]
	s_waitcnt vmcnt(6)
	v_pk_fma_f32 v[218:219], v[200:201], v[102:103], v[66:67]
	v_pk_fma_f32 v[216:217], v[194:195], v[100:101], v[64:65]
	s_waitcnt vmcnt(4)
	v_pk_fma_f32 v[212:213], v[196:197], v[114:115], v[78:79]
	v_pk_fma_f32 v[214:215], v[150:151], v[112:113], v[76:77]
	v_pk_fma_f32 v[208:209], v[182:183], v[98:99], v[74:75]
	v_pk_fma_f32 v[210:211], v[146:147], v[96:97], v[72:73]
	v_lshl_add_u64 v[68:69], v[130:131], 0, v[180:181]
	v_cvt_pk_bf16_f32 v64, v222, v223
	v_cvt_pk_bf16_f32 v65, v220, v221
	v_cvt_pk_bf16_f32 v66, v216, v217
	v_cvt_pk_bf16_f32 v67, v218, v219
	s_waitcnt vmcnt(3)
	v_pk_fma_f32 v[204:205], v[148:149], v[118:119], v[82:83]
	v_pk_fma_f32 v[206:207], v[142:143], v[116:117], v[80:81]
	s_waitcnt vmcnt(2)
	v_pk_fma_f32 v[200:201], v[144:145], v[110:111], v[86:87]
	v_pk_fma_f32 v[202:203], v[138:139], v[108:109], v[84:85]
	global_store_dwordx4 v[68:69], v[64:67], off
	s_waitcnt vmcnt(2)
	v_pk_fma_f32 v[196:197], v[140:141], v[126:127], v[90:91]
	v_pk_fma_f32 v[198:199], v[134:135], v[124:125], v[88:89]
	v_cvt_pk_bf16_f32 v64, v214, v215
	v_cvt_pk_bf16_f32 v65, v212, v213
	v_cvt_pk_bf16_f32 v66, v210, v211
	v_cvt_pk_bf16_f32 v67, v208, v209
	s_waitcnt vmcnt(1)
	v_pk_fma_f32 v[182:183], v[136:137], v[122:123], v[94:95]
	v_pk_fma_f32 v[194:195], v[132:133], v[120:121], v[92:93]
	global_store_dwordx4 v[68:69], v[64:67], off offset:1024
	s_nop 1
	v_cvt_pk_bf16_f32 v64, v206, v207
	v_cvt_pk_bf16_f32 v65, v204, v205
	v_cvt_pk_bf16_f32 v66, v202, v203
	v_cvt_pk_bf16_f32 v67, v200, v201
	global_store_dwordx4 v[68:69], v[64:67], off offset:2048
	s_nop 1
	v_cvt_pk_bf16_f32 v64, v198, v199
	v_cvt_pk_bf16_f32 v65, v196, v197
	v_cvt_pk_bf16_f32 v66, v194, v195
	v_cvt_pk_bf16_f32 v67, v182, v183
	global_store_dwordx4 v[68:69], v[64:67], off offset:3072
	s_nop 1
	v_mul_f32_e32 v64, v223, v223
	v_mul_f32_e32 v65, v221, v221
	v_fmac_f32_e32 v64, v222, v222
	v_fmac_f32_e32 v65, v220, v220
	v_add_f32_e32 v64, v64, v65
	v_mul_f32_e32 v65, v217, v217
	v_mul_f32_e32 v66, v219, v219
	v_fmac_f32_e32 v65, v216, v216
	v_fmac_f32_e32 v66, v218, v218
	v_add_f32_e32 v65, v65, v66
	v_add_f32_e32 v64, v64, v65
	v_mul_f32_e32 v65, v215, v215
	v_mul_f32_e32 v66, v213, v213
	v_fmac_f32_e32 v65, v214, v214
	v_fmac_f32_e32 v66, v212, v212
	v_add_f32_e32 v65, v65, v66
	v_add_f32_e32 v64, v64, v65
	v_mul_f32_e32 v65, v211, v211
	v_mul_f32_e32 v66, v209, v209
	v_fmac_f32_e32 v65, v210, v210
	v_fmac_f32_e32 v66, v208, v208
	v_add_f32_e32 v65, v65, v66
	v_add_f32_e32 v64, v64, v65
	v_mul_f32_e32 v65, v207, v207
	v_mul_f32_e32 v66, v205, v205
	v_fmac_f32_e32 v65, v206, v206
	v_fmac_f32_e32 v66, v204, v204
	v_add_f32_e32 v65, v65, v66
	v_add_f32_e32 v64, v64, v65
	v_mul_f32_e32 v65, v203, v203
	v_mul_f32_e32 v66, v201, v201
	v_fmac_f32_e32 v65, v202, v202
	v_fmac_f32_e32 v66, v200, v200
	v_add_f32_e32 v65, v65, v66
	v_add_f32_e32 v64, v64, v65
	v_mul_f32_e32 v65, v199, v199
	v_mul_f32_e32 v66, v197, v197
	v_fmac_f32_e32 v65, v198, v198
	v_fmac_f32_e32 v66, v196, v196
	v_add_f32_e32 v65, v65, v66
	v_add_f32_e32 v64, v64, v65
	v_mul_f32_e32 v65, v195, v195
	v_mul_f32_e32 v66, v183, v183
	v_fmac_f32_e32 v65, v194, v194
	v_fmac_f32_e32 v66, v182, v182
	v_add_f32_e32 v65, v65, v66
	v_add_f32_e32 v64, v64, v65
	s_waitcnt lgkmcnt(0)
	s_nop 1
	v_add_f32_dpp v64, v64, v64 quad_perm:[1,0,3,2] row_mask:0xf bank_mask:0xf
	s_waitcnt lgkmcnt(0)
; DI float row_rms_scale(const Row32& r) {
;     float s = 0.f;
; #pragma unroll
;     for (int i = 0; i < 8; ++i) s += (r.v[i].x * r.v[i].x + r.v[i].y * r.v[i].y) + (r.v[i].z * r.v[i].z + r.v[i].w * r.v[i].w);
;     s = wave_sum(s);
;     return 1.0f / sqrtf(s * (1.f / DM) + EPS);
; }
; DI void norm_mod_store(const Row32& x, float rs, const float* g, const float* shift, const float* scale, bf16_t* dst, int lane) {
;     Row32 gg, sh, sc, o; ld_row_f32(gg, g, lane); ld_row_f32(sh, shift, lane); ld_row_f32(sc, scale, lane);
; #pragma unroll
;     for (int i = 0; i < 8; ++i) o.v[i] = (x.v[i] * rs * gg.v[i]) * (1.f + sc.v[i]) + sh.v[i];
;     st_row_bf16(o, dst, lane);
; }
; DI void ew1(ArgsRef a, int l) {
;     ...
;         const float r2 = row_rms_scale(x);
;         norm_mod_store(x, r2, a.in[I_GPREFFN] + l * DM, md + 3 * DM, md + 4 * DM, H + hpad_row(g) * DM, lane); };
	s_nop 1
	v_add_f32_dpp v64, v64, v64 quad_perm:[2,3,0,1] row_mask:0xf bank_mask:0xf
	s_waitcnt lgkmcnt(0)
	s_nop 1
	v_add_f32_dpp v64, v64, v64 row_half_mirror row_mask:0xf bank_mask:0xf
	s_waitcnt lgkmcnt(0)
	s_nop 1
	v_add_f32_dpp v64, v64, v64 row_mirror row_mask:0xf bank_mask:0xf
	s_waitcnt lgkmcnt(0)
	v_mov_b32_e32 v65, v64
	s_nop 1
	v_permlane16_swap_b32_e32 v64, v65
	v_add_f32_e32 v66, v64, v65
	ds_bpermute_b32 v67, v246, v66
	s_and_saveexec_b64 s[0:1], s[6:7]
	s_xor_b64 s[0:1], exec, s[0:1]
	v_lshrrev_b32_e32 v64, 8, v153
	v_mul_hi_u32_u24_e32 v65, 0x102, v64
	v_mul_u32_u24_e32 v64, 0x102, v64
	s_or_saveexec_b64 s[0:1], s[0:1]
	v_mov_b32_e32 v68, 0x8011
	v_mov_b32_e32 v69, 0xff
	s_xor_b64 exec, exec, s[0:1]
	v_ashrrev_i32_e32 v64, 12, v152
	v_mul_hi_i32_i24_e32 v65, 0x1002, v64
	v_mul_i32_i24_e32 v64, 0x1002, v64
	v_mov_b32_e32 v68, 1
	v_mov_b32_e32 v69, 0xfff
	s_or_b64 exec, exec, s[0:1]
	s_waitcnt lgkmcnt(0)
	v_add_f32_e32 v66, v66, v67
	v_fmamk_f32 v66, v66, 0x3a000000, v189
	v_cmp_gt_f32_e32 vcc, s71, v66
	v_mul_f32_e32 v67, 0x4f800000, v66
	v_lshl_add_u64 v[234:235], v[128:129], 0, v[184:185]
	v_cndmask_b32_e32 v66, v66, v67, vcc
	v_sqrt_f32_e32 v67, v66
	s_nop 0
	v_add_u32_e32 v70, -1, v67
	v_fma_f32 v71, -v70, v67, v66
	v_cmp_ge_f32_e64 s[6:7], 0, v71
	v_add_u32_e32 v71, 1, v67
	s_nop 0
	v_cndmask_b32_e64 v70, v67, v70, s[6:7]
	v_fma_f32 v67, -v71, v67, v66
	v_cmp_lt_f32_e64 s[6:7], 0, v67
	s_nop 1
	v_cndmask_b32_e64 v67, v70, v71, s[6:7]
	v_mul_f32_e32 v70, 0x37800000, v67
	v_cndmask_b32_e32 v67, v67, v70, vcc
	v_cmp_class_f32_e32 vcc, v66, v227
	s_nop 1
	v_cndmask_b32_e32 v66, v67, v66, vcc
	v_div_scale_f32 v67, s[0:1], v66, v66, 1.0
	v_rcp_f32_e32 v70, v67
	s_mov_b64 s[0:1], 0x6000
	v_lshl_add_u64 v[80:81], v[234:235], 0, s[0:1]
	s_movk_i32 s0, 0x7000
	v_fma_f32 v71, -v67, v70, 1.0
	v_fmac_f32_e32 v70, v71, v70
	v_div_scale_f32 v71, vcc, 1.0, v66, 1.0
	v_mul_f32_e32 v72, v71, v70
	v_fma_f32 v73, -v67, v72, v71
	v_fmac_f32_e32 v72, v73, v70
	v_fma_f32 v67, -v67, v72, v71
	v_div_fmas_f32 v67, v67, v70, v72
	v_div_fixup_f32 v226, v67, v66, 1.0
	v_and_b32_e32 v66, v69, v152
	v_add_u32_e32 v66, v66, v68
	v_mov_b32_e32 v67, v185
	v_add_co_u32_e32 v82, vcc, s0, v234
	v_lshl_add_u64 v[64:65], v[64:65], 0, v[66:67]
	s_nop 0
	v_addc_co_u32_e32 v83, vcc, 0, v235, vcc
	s_mov_b64 s[0:1], 0x7000
	v_lshlrev_b64 v[224:225], 12, v[64:65]
	global_load_dwordx4 v[64:67], v[166:167], off offset:16
	global_load_dwordx4 v[116:119], v[166:167], off
	global_load_dwordx4 v[92:95], v[166:167], off offset:2064
	global_load_dwordx4 v[100:103], v[166:167], off offset:2048
	global_load_dwordx4 v[76:79], v[168:169], off offset:16
	global_load_dwordx4 v[84:87], v[168:169], off
	global_load_dwordx4 v[68:71], v[170:171], off offset:16
	global_load_dwordx4 v[72:75], v[170:171], off
	global_load_dwordx4 v[124:127], v[82:83], off offset:-4096
	global_load_dwordx4 v[120:123], v[80:81], off offset:16
	global_load_dwordx4 v[108:111], v[80:81], off offset:2064
	global_load_dwordx4 v[112:115], v[80:81], off offset:2048
	v_lshl_add_u64 v[80:81], v[234:235], 0, s[0:1]
	s_mov_b64 s[0:1], 0x7800
	global_load_dwordx4 v[104:107], v[82:83], off
	global_load_dwordx4 v[96:99], v[80:81], off offset:16
	v_lshl_add_u64 v[80:81], v[234:235], 0, s[0:1]
	s_mov_b64 s[0:1], 0x8000
	v_lshl_add_u64 v[136:137], v[234:235], 0, s[0:1]
	s_mov_b32 s0, 0x9000
	v_add_co_u32_e32 v236, vcc, s0, v234
	global_load_dwordx4 v[88:91], v[82:83], off offset:2048
	s_nop 0
	global_load_dwordx4 v[80:83], v[80:81], off offset:16
	v_addc_co_u32_e32 v237, vcc, 0, v235, vcc
	global_load_dwordx4 v[144:147], v[236:237], off offset:-4096
	global_load_dwordx4 v[132:135], v[136:137], off offset:16
	global_load_dwordx4 v[128:131], v[136:137], off offset:2064
	s_nop 0
	global_load_dwordx4 v[136:139], v[136:137], off offset:2048
	s_mov_b64 s[0:1], 0x9000
	v_lshl_add_u64 v[140:141], v[234:235], 0, s[0:1]
	global_load_dwordx4 v[148:151], v[236:237], off
	s_nop 0
	global_load_dwordx4 v[140:143], v[140:141], off offset:16
	s_mov_b64 s[0:1], 0x9800
	v_lshl_add_u64 v[248:249], v[234:235], 0, s[0:1]
	global_load_dwordx4 v[234:237], v[236:237], off offset:2048
	s_nop 0
	global_load_dwordx4 v[248:251], v[248:249], off offset:16
	v_pk_mul_f32 v[220:221], v[220:221], v[226:227] op_sel_hi:[1,0]
	v_pk_mul_f32 v[222:223], v[222:223], v[226:227] op_sel_hi:[1,0]
	s_waitcnt vmcnt(22)
	v_pk_mul_f32 v[118:119], v[220:221], v[118:119]
	v_pk_mul_f32 v[116:117], v[222:223], v[116:117]
	s_waitcnt vmcnt(7)
	v_pk_add_f32 v[146:147], v[146:147], 1.0 op_sel_hi:[1,0]
	v_pk_add_f32 v[144:145], v[144:145], 1.0 op_sel_hi:[1,0]
	v_pk_fma_f32 v[118:119], v[118:119], v[146:147], v[126:127]
	v_pk_fma_f32 v[116:117], v[116:117], v[144:145], v[124:125]
	v_pk_mul_f32 v[124:125], v[218:219], v[226:227] op_sel_hi:[1,0]
	v_pk_mul_f32 v[126:127], v[216:217], v[226:227] op_sel_hi:[1,0]
	v_pk_mul_f32 v[66:67], v[124:125], v[66:67]
	v_pk_mul_f32 v[64:65], v[126:127], v[64:65]
	s_waitcnt vmcnt(6)
	v_pk_add_f32 v[124:125], v[134:135], 1.0 op_sel_hi:[1,0]
	v_pk_add_f32 v[126:127], v[132:133], 1.0 op_sel_hi:[1,0]
	v_pk_fma_f32 v[122:123], v[66:67], v[124:125], v[122:123]
	v_pk_fma_f32 v[66:67], v[64:65], v[126:127], v[120:121]
	v_pk_mul_f32 v[64:65], v[212:213], v[226:227] op_sel_hi:[1,0]
	v_pk_mul_f32 v[120:121], v[214:215], v[226:227] op_sel_hi:[1,0]
	v_pk_mul_f32 v[64:65], v[64:65], v[102:103]
	v_pk_mul_f32 v[100:101], v[120:121], v[100:101]
	s_waitcnt vmcnt(4)
; DI void norm_mod_store(const Row32& x, float rs, const float* g, const float* shift, const float* scale, bf16_t* dst, int lane) {
;     Row32 gg, sh, sc, o; ld_row_f32(gg, g, lane); ld_row_f32(sh, shift, lane); ld_row_f32(sc, scale, lane);
; #pragma unroll
;     for (int i = 0; i < 8; ++i) o.v[i] = (x.v[i] * rs * gg.v[i]) * (1.f + sc.v[i]) + sh.v[i];
;     st_row_bf16(o, dst, lane);
; }
; DI void ew1(ArgsRef a, int l) {
;     ...
;         norm_mod_store(x, r2, a.in[I_GPREFFN] + l * DM, md + 3 * DM, md + 4 * DM, H + hpad_row(g) * DM, lane); };
;     for (int g = gw; g < nrows; g += 2 * NGW) {
;         const int g2 = g + NGW; const bool has2 = g2 < nrows;
;         Row32 mxA, xA, mxB, xB;
;         load(g, mxA, xA);
;         if (has2) load(g2, mxB, xB);
;         finish(g, mxA, xA);
;         if (has2) finish(g2, mxB, xB);
	v_pk_add_f32 v[102:103], v[138:139], 1.0 op_sel_hi:[1,0]
	v_pk_add_f32 v[120:121], v[136:137], 1.0 op_sel_hi:[1,0]
	v_pk_fma_f32 v[102:103], v[64:65], v[102:103], v[114:115]
	v_pk_fma_f32 v[100:101], v[100:101], v[120:121], v[112:113]
	v_pk_mul_f32 v[64:65], v[208:209], v[226:227] op_sel_hi:[1,0]
	v_pk_mul_f32 v[112:113], v[210:211], v[226:227] op_sel_hi:[1,0]
	v_pk_mul_f32 v[64:65], v[64:65], v[94:95]
	v_pk_mul_f32 v[92:93], v[112:113], v[92:93]
	v_pk_add_f32 v[94:95], v[130:131], 1.0 op_sel_hi:[1,0]
	v_pk_add_f32 v[112:113], v[128:129], 1.0 op_sel_hi:[1,0]
	v_pk_fma_f32 v[94:95], v[64:65], v[94:95], v[110:111]
	v_pk_fma_f32 v[92:93], v[92:93], v[112:113], v[108:109]
	v_pk_mul_f32 v[64:65], v[204:205], v[226:227] op_sel_hi:[1,0]
	v_pk_mul_f32 v[108:109], v[206:207], v[226:227] op_sel_hi:[1,0]
	v_pk_mul_f32 v[64:65], v[64:65], v[86:87]
	v_pk_mul_f32 v[84:85], v[108:109], v[84:85]
	s_waitcnt vmcnt(3)
	v_pk_add_f32 v[86:87], v[150:151], 1.0 op_sel_hi:[1,0]
	v_pk_add_f32 v[108:109], v[148:149], 1.0 op_sel_hi:[1,0]
	v_pk_fma_f32 v[86:87], v[64:65], v[86:87], v[106:107]
	v_pk_fma_f32 v[84:85], v[84:85], v[108:109], v[104:105]
	v_pk_mul_f32 v[64:65], v[200:201], v[226:227] op_sel_hi:[1,0]
	v_pk_mul_f32 v[104:105], v[202:203], v[226:227] op_sel_hi:[1,0]
	v_pk_mul_f32 v[64:65], v[64:65], v[78:79]
	v_pk_mul_f32 v[76:77], v[104:105], v[76:77]
	s_waitcnt vmcnt(2)
	v_pk_add_f32 v[78:79], v[142:143], 1.0 op_sel_hi:[1,0]
	v_pk_add_f32 v[104:105], v[140:141], 1.0 op_sel_hi:[1,0]
	v_pk_fma_f32 v[78:79], v[64:65], v[78:79], v[98:99]
	v_pk_fma_f32 v[76:77], v[76:77], v[104:105], v[96:97]
	v_pk_mul_f32 v[64:65], v[196:197], v[226:227] op_sel_hi:[1,0]
	v_pk_mul_f32 v[96:97], v[198:199], v[226:227] op_sel_hi:[1,0]
	v_pk_mul_f32 v[64:65], v[64:65], v[74:75]
	v_pk_mul_f32 v[72:73], v[96:97], v[72:73]
	s_waitcnt vmcnt(1)
	v_pk_add_f32 v[74:75], v[236:237], 1.0 op_sel_hi:[1,0]
	v_pk_add_f32 v[96:97], v[234:235], 1.0 op_sel_hi:[1,0]
	v_pk_fma_f32 v[74:75], v[64:65], v[74:75], v[90:91]
	v_pk_fma_f32 v[72:73], v[72:73], v[96:97], v[88:89]
	v_pk_mul_f32 v[64:65], v[182:183], v[226:227] op_sel_hi:[1,0]
	v_pk_mul_f32 v[88:89], v[194:195], v[226:227] op_sel_hi:[1,0]
	v_pk_mul_f32 v[64:65], v[64:65], v[70:71]
	v_pk_mul_f32 v[68:69], v[88:89], v[68:69]
	s_waitcnt vmcnt(0)
	v_pk_add_f32 v[70:71], v[250:251], 1.0 op_sel_hi:[1,0]
	v_pk_add_f32 v[88:89], v[248:249], 1.0 op_sel_hi:[1,0]
	v_pk_fma_f32 v[70:71], v[64:65], v[70:71], v[82:83]
	v_pk_fma_f32 v[68:69], v[68:69], v[88:89], v[80:81]
	v_lshl_add_u64 v[80:81], v[172:173], 0, v[224:225]
	v_cvt_pk_bf16_f32 v64, v116, v117
	v_cvt_pk_bf16_f32 v65, v118, v119
	v_cvt_pk_bf16_f32 v66, v66, v67
	v_cvt_pk_bf16_f32 v67, v122, v123
	global_store_dwordx4 v[80:81], v[64:67], off
	s_nop 1
	v_cvt_pk_bf16_f32 v64, v100, v101
	v_cvt_pk_bf16_f32 v65, v102, v103
	v_cvt_pk_bf16_f32 v66, v92, v93
	v_cvt_pk_bf16_f32 v67, v94, v95
	global_store_dwordx4 v[80:81], v[64:67], off offset:1024
	s_nop 1
	v_cvt_pk_bf16_f32 v64, v84, v85
	v_cvt_pk_bf16_f32 v65, v86, v87
	v_cvt_pk_bf16_f32 v66, v76, v77
	v_cvt_pk_bf16_f32 v67, v78, v79
	global_store_dwordx4 v[80:81], v[64:67], off offset:2048
	s_nop 1
	v_cvt_pk_bf16_f32 v64, v72, v73
	v_cvt_pk_bf16_f32 v65, v74, v75
	v_cvt_pk_bf16_f32 v66, v68, v69
	v_cvt_pk_bf16_f32 v67, v70, v71
	global_store_dwordx4 v[80:81], v[64:67], off offset:3072
	s_and_saveexec_b64 s[0:1], s[8:9]
	s_cbranch_execz .LBB0_154
	v_cmp_gt_i32_e32 vcc, s87, v178
	v_add_u32_e32 v100, 0xffff8000, v178
	v_ashrrev_i32_e32 v64, 31, v178
	v_mov_b32_e32 v66, s97
	v_mov_b32_e32 v67, s17
	v_cndmask_b32_e32 v65, 0, v64, vcc
	v_cndmask_b32_e32 v64, v100, v178, vcc
	v_cndmask_b32_e32 v67, v66, v67, vcc
	v_mov_b32_e32 v66, s96
	v_mov_b32_e32 v68, s16
	v_cndmask_b32_e32 v66, v66, v68, vcc
	v_lshlrev_b64 v[64:65], 13, v[64:65]
	v_mov_b32_e32 v68, v5
	v_mov_b32_e32 v69, v1
	v_lshl_add_u64 v[96:97], v[66:67], 0, v[64:65]
	v_mov_b32_e32 v66, v4
	v_mov_b32_e32 v67, v0
	v_pk_mul_f32 v[68:69], v[68:69], v[68:69]
	v_mov_b32_e32 v70, v7
	v_mov_b32_e32 v71, v3
	v_pk_fma_f32 v[66:67], v[66:67], v[66:67], v[68:69]
	v_mov_b32_e32 v68, v6
	v_mov_b32_e32 v69, v2
	v_pk_mul_f32 v[70:71], v[70:71], v[70:71]
	v_min_i32_e32 v64, 0x8000, v178
	v_pk_fma_f32 v[68:69], v[68:69], v[68:69], v[70:71]
	v_pk_mul_f32 v[70:71], v[8:9], v[8:9]
	v_pk_add_f32 v[66:67], v[66:67], v[68:69]
	v_pk_mul_f32 v[68:69], v[10:11], v[10:11]
	v_pk_add_f32 v[66:67], v[66:67], v[66:67] op_sel_hi:[0,1]
	v_pk_mov_b32 v[72:73], v[70:71], v[68:69] op_sel:[1,0]
	v_mov_b32_e32 v71, v69
	v_mul_f32_e32 v66, v12, v12
	v_pk_add_f32 v[68:69], v[72:73], v[70:71]
	v_pk_fma_f32 v[70:71], v[12:13], v[12:13], v[66:67] op_sel_hi:[1,1,0]
	v_mul_f32_e32 v66, v14, v14
	v_pk_add_f32 v[68:69], v[68:69], v[68:69] op_sel_hi:[0,1]
	v_pk_fma_f32 v[72:73], v[14:15], v[14:15], v[66:67] op_sel_hi:[1,1,0]
	v_mul_f32_e32 v70, v16, v16
	v_mul_f32_e32 v72, v17, v17
	v_mul_f32_e32 v68, v18, v18
	v_mul_f32_e32 v66, v19, v19
	v_pk_add_f32 v[70:71], v[70:71], v[72:73]
	v_pk_add_f32 v[66:67], v[68:69], v[66:67]
	v_pk_mul_f32 v[68:69], v[22:23], v[22:23]
	v_pk_add_f32 v[66:67], v[70:71], v[66:67]
	v_pk_mul_f32 v[70:71], v[20:21], v[20:21]
	v_pk_add_f32 v[66:67], v[66:67], v[66:67] op_sel_hi:[0,1]
	v_pk_mov_b32 v[72:73], v[70:71], v[68:69] op_sel:[1,0]
	v_mov_b32_e32 v71, v69
	v_mul_f32_e32 v66, v24, v24
	v_pk_add_f32 v[68:69], v[72:73], v[70:71]
	v_pk_fma_f32 v[70:71], v[24:25], v[24:25], v[66:67] op_sel_hi:[1,1,0]
	v_mul_f32_e32 v66, v26, v26
	v_pk_add_f32 v[68:69], v[68:69], v[68:69] op_sel_hi:[0,1]
	v_pk_fma_f32 v[72:73], v[26:27], v[26:27], v[66:67] op_sel_hi:[1,1,0]
	v_mul_f32_e32 v70, v28, v28
	v_mul_f32_e32 v72, v29, v29
	v_mul_f32_e32 v68, v30, v30
	v_mul_f32_e32 v66, v31, v31
	v_pk_add_f32 v[70:71], v[70:71], v[72:73]
	v_pk_add_f32 v[66:67], v[68:69], v[66:67]
	v_ashrrev_i32_e32 v64, 12, v64
	v_pk_add_f32 v[66:67], v[70:71], v[66:67]
	v_mul_hi_i32_i24_e32 v65, 0xc000, v64
	v_add_f32_e32 v66, v66, v67
	v_mul_i32_i24_e32 v64, 0xc000, v64
	v_mov_b32_e32 v181, v185
	v_cmp_lt_i32_e64 s[6:7], s63, v178
	s_waitcnt lgkmcnt(0)
; DI float row_rms_scale(const Row32& r) {
;     float s = 0.f;
; #pragma unroll
;     for (int i = 0; i < 8; ++i) s += (r.v[i].x * r.v[i].x + r.v[i].y * r.v[i].y) + (r.v[i].z * r.v[i].z + r.v[i].w * r.v[i].w);
;     s = wave_sum(s);
;     return 1.0f / sqrtf(s * (1.f / DM) + EPS);
; DI void ew1(ArgsRef a, int l) {
;     ...
;         const float r1 = row_rms_scale(mx);
;         ld_row_f32(t, a.in[I_GPOSTMIX] + l * DM, lane);
; #pragma unroll
;         for (int i = 0; i < 8; ++i) mx.v[i] = mx.v[i] * r1 * t.v[i];
;         ld_row_f32(t, md + 2 * DM, lane);
; #pragma unroll
;         for (int i = 0; i < 8; ++i) x.v[i] = x.v[i] + t.v[i] * mx.v[i];
	s_nop 1
	v_add_f32_dpp v66, v66, v66 quad_perm:[1,0,3,2] row_mask:0xf bank_mask:0xf
	s_waitcnt lgkmcnt(0)
	s_nop 1
	v_add_f32_dpp v66, v66, v66 quad_perm:[2,3,0,1] row_mask:0xf bank_mask:0xf
	s_waitcnt lgkmcnt(0)
	s_nop 1
	v_add_f32_dpp v66, v66, v66 row_half_mirror row_mask:0xf bank_mask:0xf
	s_waitcnt lgkmcnt(0)
	s_nop 1
	v_add_f32_dpp v66, v66, v66 row_mirror row_mask:0xf bank_mask:0xf
	s_waitcnt lgkmcnt(0)
	v_mov_b32_e32 v67, v66
	s_nop 1
	v_permlane16_swap_b32_e32 v66, v67
	v_add_f32_e32 v66, v66, v67
	s_waitcnt lgkmcnt(0)
	v_mov_b32_e32 v67, v66
	s_nop 1
	v_permlane32_swap_b32_e32 v66, v67
	v_add_f32_e32 v66, v66, v67
	v_fmamk_f32 v66, v66, 0x3a000000, v189
	v_cmp_gt_f32_e32 vcc, s71, v66
	v_mul_f32_e32 v67, 0x4f800000, v66
	s_nop 0
	v_cndmask_b32_e32 v66, v66, v67, vcc
	v_sqrt_f32_e32 v67, v66
	s_nop 0
	v_add_u32_e32 v68, -1, v67
	v_fma_f32 v69, -v68, v67, v66
	v_cmp_ge_f32_e64 s[8:9], 0, v69
	v_add_u32_e32 v69, 1, v67
	s_nop 0
	v_cndmask_b32_e64 v68, v67, v68, s[8:9]
	v_fma_f32 v67, -v69, v67, v66
	v_cmp_lt_f32_e64 s[8:9], 0, v67
	s_nop 1
	v_cndmask_b32_e64 v67, v68, v69, s[8:9]
	v_mul_f32_e32 v68, 0x37800000, v67
	v_cndmask_b32_e32 v67, v67, v68, vcc
	v_cmp_class_f32_e32 vcc, v66, v227
	s_nop 1
	v_cndmask_b32_e32 v66, v67, v66, vcc
	v_div_scale_f32 v67, s[8:9], v66, v66, 1.0
	v_rcp_f32_e32 v68, v67
	v_readlane_b32 s8, v254, 34
	v_readlane_b32 s9, v254, 35
	v_fma_f32 v69, -v67, v68, 1.0
	v_fmac_f32_e32 v68, v69, v68
	v_div_scale_f32 v69, vcc, 1.0, v66, 1.0
	v_mul_f32_e32 v70, v69, v68
	v_fma_f32 v71, -v67, v70, v69
	v_fmac_f32_e32 v70, v71, v68
	v_fma_f32 v67, -v67, v70, v69
	v_div_fmas_f32 v67, v67, v68, v70
	v_div_fixup_f32 v94, v67, v66, 1.0
	global_load_dwordx4 v[66:69], v[160:161], off offset:16
	global_load_dwordx4 v[70:73], v[160:161], off
	global_load_dwordx4 v[74:77], v[160:161], off offset:2064
	global_load_dwordx4 v[78:81], v[160:161], off offset:2048
	global_load_dwordx4 v[82:85], v[162:163], off offset:16
	global_load_dwordx4 v[86:89], v[162:163], off
	global_load_dwordx4 v[90:93], v[164:165], off offset:16
	global_load_dwordx4 v[102:105], v[164:165], off
	v_pk_mul_f32 v[18:19], v[94:95], v[18:19] op_sel_hi:[0,1]
	v_lshl_add_u64 v[98:99], s[8:9], 0, v[64:65]
	v_pk_mul_f32 v[14:15], v[94:95], v[14:15] op_sel_hi:[0,1]
	s_mov_b64 s[8:9], 0x4000
	v_pk_mul_f32 v[28:29], v[94:95], v[28:29] op_sel_hi:[0,1]
	v_pk_mul_f32 v[0:1], v[94:95], v[0:1] op_sel_hi:[0,1]
	v_pk_mul_f32 v[2:3], v[94:95], v[2:3] op_sel_hi:[0,1]
	v_pk_mul_f32 v[4:5], v[94:95], v[4:5] op_sel_hi:[0,1]
	v_pk_mul_f32 v[6:7], v[94:95], v[6:7] op_sel_hi:[0,1]
	v_pk_mul_f32 v[10:11], v[94:95], v[10:11] op_sel_hi:[0,1]
	v_pk_mul_f32 v[12:13], v[94:95], v[12:13] op_sel_hi:[0,1]
	v_pk_mul_f32 v[20:21], v[94:95], v[20:21] op_sel_hi:[0,1]
	v_pk_mul_f32 v[8:9], v[94:95], v[8:9] op_sel_hi:[0,1]
	v_pk_mul_f32 v[16:17], v[94:95], v[16:17] op_sel_hi:[0,1]
	v_pk_mul_f32 v[22:23], v[94:95], v[22:23] op_sel_hi:[0,1]
	v_pk_mul_f32 v[30:31], v[94:95], v[30:31] op_sel_hi:[0,1]
	v_pk_mul_f32 v[24:25], v[94:95], v[24:25] op_sel_hi:[0,1]
	v_pk_mul_f32 v[26:27], v[94:95], v[26:27] op_sel_hi:[0,1]
	s_waitcnt vmcnt(7)
	v_pk_mul_f32 v[6:7], v[68:69], v[6:7]
	s_waitcnt vmcnt(6)
	v_pk_mul_f32 v[2:3], v[72:73], v[2:3]
	s_waitcnt vmcnt(5)
	v_pk_mul_f32 v[14:15], v[76:77], v[14:15]
	v_pk_mul_f32 v[0:1], v[70:71], v[0:1]
	v_pk_mul_f32 v[4:5], v[66:67], v[4:5]
	s_waitcnt vmcnt(2)
	v_pk_mul_f32 v[18:19], v[88:89], v[18:19]
	v_lshl_add_u64 v[88:89], v[98:99], 0, v[184:185]
	v_lshl_add_u64 v[76:77], v[88:89], 0, s[8:9]
	s_movk_i32 s8, 0x5000
	s_waitcnt vmcnt(1)
	v_pk_mul_f32 v[28:29], v[90:91], v[28:29]
	v_add_co_u32_e32 v90, vcc, s8, v88
	s_mov_b64 s[8:9], 0x5000
	s_nop 0
	v_addc_co_u32_e32 v91, vcc, 0, v89, vcc
	v_pk_mul_f32 v[10:11], v[80:81], v[10:11]
	v_pk_mul_f32 v[12:13], v[74:75], v[12:13]
	v_pk_mul_f32 v[20:21], v[82:83], v[20:21]
	global_load_dwordx4 v[72:75], v[90:91], off offset:-4096
	global_load_dwordx4 v[68:71], v[76:77], off offset:16
	global_load_dwordx4 v[64:67], v[76:77], off offset:2064
	global_load_dwordx4 v[80:83], v[76:77], off offset:2048
	v_lshl_add_u64 v[76:77], v[88:89], 0, s[8:9]
	s_mov_b64 s[8:9], 0x5800
	v_pk_mul_f32 v[8:9], v[78:79], v[8:9]
	v_pk_mul_f32 v[16:17], v[86:87], v[16:17]
	v_pk_mul_f32 v[22:23], v[84:85], v[22:23]
	global_load_dwordx4 v[84:87], v[90:91], off
	s_nop 0
	global_load_dwordx4 v[76:79], v[76:77], off offset:16
	v_lshl_add_u64 v[88:89], v[88:89], 0, s[8:9]
	v_pk_mul_f32 v[30:31], v[92:93], v[30:31]
	global_load_dwordx4 v[92:95], v[90:91], off offset:2048
	s_nop 0
	global_load_dwordx4 v[88:91], v[88:89], off offset:16
	s_waitcnt vmcnt(8)
; DI void ew1(ArgsRef a, int l) {
;     ...
;         for (int i = 0; i < 8; ++i) x.v[i] = x.v[i] + t.v[i] * mx.v[i];
;         st_row_bf16(x, (bf16_t*)xo, lane);
;         const float r2 = row_rms_scale(x);
;         norm_mod_store(x, r2, a.in[I_GPREFFN] + l * DM, md + 3 * DM, md + 4 * DM, H + hpad_row(g) * DM, lane); };
	v_pk_mul_f32 v[26:27], v[104:105], v[26:27]
	v_pk_mul_f32 v[24:25], v[102:103], v[24:25]
	s_waitcnt vmcnt(7)
	v_pk_fma_f32 v[34:35], v[74:75], v[2:3], v[34:35]
	v_pk_fma_f32 v[32:33], v[72:73], v[0:1], v[32:33]
	s_waitcnt vmcnt(6)
	v_pk_fma_f32 v[38:39], v[70:71], v[6:7], v[38:39]
	v_pk_fma_f32 v[36:37], v[68:69], v[4:5], v[36:37]
	s_waitcnt vmcnt(4)
	v_pk_fma_f32 v[42:43], v[10:11], v[82:83], v[42:43]
	v_pk_fma_f32 v[40:41], v[8:9], v[80:81], v[40:41]
	v_pk_fma_f32 v[46:47], v[14:15], v[66:67], v[46:47]
	v_pk_fma_f32 v[44:45], v[12:13], v[64:65], v[44:45]
	v_lshl_add_u64 v[68:69], v[96:97], 0, v[180:181]
	v_cvt_pk_bf16_f32 v64, v32, v33
	v_cvt_pk_bf16_f32 v65, v34, v35
	v_cvt_pk_bf16_f32 v66, v36, v37
	v_cvt_pk_bf16_f32 v67, v38, v39
	s_waitcnt vmcnt(3)
	v_pk_fma_f32 v[50:51], v[18:19], v[86:87], v[50:51]
	v_pk_fma_f32 v[48:49], v[16:17], v[84:85], v[48:49]
	s_waitcnt vmcnt(2)
	v_pk_fma_f32 v[54:55], v[22:23], v[78:79], v[54:55]
	v_pk_fma_f32 v[52:53], v[20:21], v[76:77], v[52:53]
	global_store_dwordx4 v[68:69], v[64:67], off
	s_waitcnt vmcnt(2)
	v_pk_fma_f32 v[58:59], v[26:27], v[94:95], v[58:59]
	v_pk_fma_f32 v[56:57], v[24:25], v[92:93], v[56:57]
	v_cvt_pk_bf16_f32 v64, v40, v41
	v_cvt_pk_bf16_f32 v65, v42, v43
	v_cvt_pk_bf16_f32 v66, v44, v45
	v_cvt_pk_bf16_f32 v67, v46, v47
	s_waitcnt vmcnt(1)
	v_pk_fma_f32 v[62:63], v[30:31], v[90:91], v[62:63]
	v_pk_fma_f32 v[60:61], v[28:29], v[88:89], v[60:61]
	global_store_dwordx4 v[68:69], v[64:67], off offset:1024
	s_nop 1
	v_cvt_pk_bf16_f32 v64, v48, v49
	v_cvt_pk_bf16_f32 v65, v50, v51
	v_cvt_pk_bf16_f32 v66, v52, v53
	v_cvt_pk_bf16_f32 v67, v54, v55
	global_store_dwordx4 v[68:69], v[64:67], off offset:2048
	s_nop 1
	v_cvt_pk_bf16_f32 v64, v56, v57
	v_cvt_pk_bf16_f32 v65, v58, v59
	v_cvt_pk_bf16_f32 v66, v60, v61
	v_cvt_pk_bf16_f32 v67, v62, v63
	global_store_dwordx4 v[68:69], v[64:67], off offset:3072
	s_nop 1
	v_mul_f32_e32 v64, v33, v33
	v_mul_f32_e32 v65, v35, v35
	v_fmac_f32_e32 v64, v32, v32
	v_fmac_f32_e32 v65, v34, v34
	v_add_f32_e32 v64, v64, v65
	v_mul_f32_e32 v65, v37, v37
	v_mul_f32_e32 v66, v39, v39
	v_fmac_f32_e32 v65, v36, v36
	v_fmac_f32_e32 v66, v38, v38
	v_add_f32_e32 v65, v65, v66
	v_add_f32_e32 v64, v64, v65
	v_mul_f32_e32 v65, v41, v41
	v_mul_f32_e32 v66, v43, v43
	v_fmac_f32_e32 v65, v40, v40
	v_fmac_f32_e32 v66, v42, v42
	v_add_f32_e32 v65, v65, v66
	v_add_f32_e32 v64, v64, v65
	v_mul_f32_e32 v65, v45, v45
	v_mul_f32_e32 v66, v47, v47
	v_fmac_f32_e32 v65, v44, v44
	v_fmac_f32_e32 v66, v46, v46
	v_add_f32_e32 v65, v65, v66
	v_add_f32_e32 v64, v64, v65
	v_mul_f32_e32 v65, v49, v49
	v_mul_f32_e32 v66, v51, v51
	v_fmac_f32_e32 v65, v48, v48
	v_fmac_f32_e32 v66, v50, v50
	v_add_f32_e32 v65, v65, v66
	v_add_f32_e32 v64, v64, v65
	v_mul_f32_e32 v65, v53, v53
	v_mul_f32_e32 v66, v55, v55
	v_fmac_f32_e32 v65, v52, v52
	v_fmac_f32_e32 v66, v54, v54
	v_add_f32_e32 v65, v65, v66
	v_add_f32_e32 v64, v64, v65
	v_mul_f32_e32 v65, v57, v57
	v_mul_f32_e32 v66, v59, v59
	v_fmac_f32_e32 v65, v56, v56
	v_fmac_f32_e32 v66, v58, v58
	v_add_f32_e32 v65, v65, v66
	v_add_f32_e32 v64, v64, v65
	v_mul_f32_e32 v65, v61, v61
	v_mul_f32_e32 v66, v63, v63
	v_fmac_f32_e32 v65, v60, v60
	v_fmac_f32_e32 v66, v62, v62
	v_add_f32_e32 v65, v65, v66
	v_add_f32_e32 v64, v64, v65
	s_waitcnt lgkmcnt(0)
	s_nop 1
	v_add_f32_dpp v64, v64, v64 quad_perm:[1,0,3,2] row_mask:0xf bank_mask:0xf
	s_waitcnt lgkmcnt(0)
	s_nop 1
	v_add_f32_dpp v64, v64, v64 quad_perm:[2,3,0,1] row_mask:0xf bank_mask:0xf
	s_waitcnt lgkmcnt(0)
	s_nop 1
	v_add_f32_dpp v64, v64, v64 row_half_mirror row_mask:0xf bank_mask:0xf
	s_waitcnt lgkmcnt(0)
	s_nop 1
	v_add_f32_dpp v64, v64, v64 row_mirror row_mask:0xf bank_mask:0xf
	s_waitcnt lgkmcnt(0)
	v_mov_b32_e32 v65, v64
	s_nop 1
	v_permlane16_swap_b32_e32 v64, v65
	v_add_f32_e32 v66, v64, v65
	ds_bpermute_b32 v67, v246, v66
	s_and_saveexec_b64 s[8:9], s[6:7]
	s_xor_b64 s[6:7], exec, s[8:9]
	v_lshrrev_b32_e32 v64, 8, v100
	v_mul_hi_u32_u24_e32 v65, 0x102, v64
	v_mul_u32_u24_e32 v64, 0x102, v64
	s_or_saveexec_b64 s[6:7], s[6:7]
	v_mov_b32_e32 v68, 0x8011
	v_mov_b32_e32 v69, 0xff
	s_xor_b64 exec, exec, s[6:7]
	s_cbranch_execz .LBB0_153
	v_ashrrev_i32_e32 v64, 12, v178
	v_mul_hi_i32_i24_e32 v65, 0x1002, v64
	v_mul_i32_i24_e32 v64, 0x1002, v64
	v_mov_b32_e32 v68, 1
	v_mov_b32_e32 v69, 0xfff
	s_branch .LBB0_153

; DI void ld_row_bf16(Row32& r, const bf16_t* p, int lane) {
; #pragma unroll
;     for (int j = 0; j < 4; ++j) { const u32x4 w = *(const u32x4*)(p + j * 512 + lane * 8);
;         r.v[2 * j] = (f32x4){bflo(w.x), bfhi(w.x), bflo(w.y), bfhi(w.y)}; r.v[2 * j + 1] = (f32x4){bflo(w.z), bfhi(w.z), bflo(w.w), bfhi(w.w)}; }
; }
; DI void ew2(ArgsRef a, int l) {
;     ...
;     auto load = [&](int g, Row32& y, Row32& x) {
;         if (g < MLAT) ld_row_bf16(y, Y + (size_t)g * DM, lane); else ld_row_part4(y, (const float*)(a.ws + WS_PART) + (size_t)(g - MLAT) * DM, lane);
;         ld_row_bf16(x, (const bf16_t*)xrow(g), lane); };
;     auto finish = [&](int g, Row32& y, Row32& x) {
;         float* xo = xrow(g);
;         const float* md = MODS + (size_t)row_mod_idx(g) * NMODS;
;         Row32 t;
;         const float r1 = row_rms_scale(y);
.LBB0_461:
	s_or_b64 exec, exec, s[12:13]
	s_waitcnt vmcnt(0)
	v_lshlrev_b32_e32 v132, 16, v108
	v_and_b32_e32 v133, 0xffff0000, v108
	v_lshlrev_b32_e32 v134, 16, v109
	v_and_b32_e32 v135, 0xffff0000, v109
	v_lshlrev_b32_e32 v120, 16, v106
	v_and_b32_e32 v121, 0xffff0000, v106
	v_lshlrev_b32_e32 v122, 16, v107
	v_and_b32_e32 v123, 0xffff0000, v107
	v_lshlrev_b32_e32 v106, 16, v96
	v_and_b32_e32 v107, 0xffff0000, v96
	v_lshlrev_b32_e32 v108, 16, v97
	v_and_b32_e32 v109, 0xffff0000, v97
	v_mov_b32_e32 v96, s97
	v_mov_b32_e32 v97, s15
	v_lshlrev_b32_e32 v128, 16, v110
	v_and_b32_e32 v129, 0xffff0000, v110
	v_lshlrev_b32_e32 v130, 16, v111
	v_and_b32_e32 v131, 0xffff0000, v111
	v_lshlrev_b32_e32 v110, 16, v102
	v_and_b32_e32 v111, 0xffff0000, v102
	v_lshlrev_b32_e32 v114, 16, v103
	v_and_b32_e32 v115, 0xffff0000, v103
	v_lshlrev_b32_e32 v102, 16, v98
	v_and_b32_e32 v103, 0xffff0000, v98
	v_cndmask_b32_e64 v97, v96, v97, s[10:11]
	v_mov_b32_e32 v96, s96
	v_mov_b32_e32 v98, s14
	v_cndmask_b32_e64 v96, v96, v98, s[10:11]
	v_lshlrev_b32_e32 v116, 16, v100
	v_and_b32_e32 v117, 0xffff0000, v100
	v_lshlrev_b32_e32 v118, 16, v101
	v_and_b32_e32 v119, 0xffff0000, v101
	v_lshl_add_u64 v[100:101], v[96:97], 0, v[112:113]
	v_mov_b32_e32 v112, v69
	v_mov_b32_e32 v113, v65
	v_lshlrev_b32_e32 v124, 16, v104
	v_and_b32_e32 v125, 0xffff0000, v104
	v_lshlrev_b32_e32 v126, 16, v105
	v_and_b32_e32 v127, 0xffff0000, v105
	v_lshlrev_b32_e32 v104, 16, v99
	v_and_b32_e32 v105, 0xffff0000, v99
	v_mov_b32_e32 v98, v68
	v_mov_b32_e32 v99, v64
	v_pk_mul_f32 v[112:113], v[112:113], v[112:113]
	v_mov_b32_e32 v136, v71
	v_mov_b32_e32 v137, v67
	v_pk_fma_f32 v[98:99], v[98:99], v[98:99], v[112:113]
	v_mov_b32_e32 v112, v70
	v_mov_b32_e32 v113, v66
	v_pk_mul_f32 v[136:137], v[136:137], v[136:137]
	v_min_i32_e32 v96, 0x8000, v194
	v_pk_fma_f32 v[112:113], v[112:113], v[112:113], v[136:137]
	v_pk_mul_f32 v[136:137], v[72:73], v[72:73]
	v_pk_add_f32 v[98:99], v[98:99], v[112:113]
	v_pk_mul_f32 v[112:113], v[74:75], v[74:75]
	v_pk_add_f32 v[98:99], v[98:99], v[98:99] op_sel_hi:[0,1]
	v_pk_mov_b32 v[138:139], v[136:137], v[112:113] op_sel:[1,0]
	v_mov_b32_e32 v137, v113
	v_mul_f32_e32 v98, v76, v76
	v_pk_add_f32 v[112:113], v[138:139], v[136:137]
	v_pk_fma_f32 v[136:137], v[76:77], v[76:77], v[98:99] op_sel_hi:[1,1,0]
	v_mul_f32_e32 v98, v78, v78
	v_pk_add_f32 v[112:113], v[112:113], v[112:113] op_sel_hi:[0,1]
	v_pk_fma_f32 v[138:139], v[78:79], v[78:79], v[98:99] op_sel_hi:[1,1,0]
	v_mul_f32_e32 v136, v80, v80
	v_mul_f32_e32 v138, v81, v81
	v_mul_f32_e32 v112, v82, v82
	v_mul_f32_e32 v98, v83, v83
	v_pk_add_f32 v[136:137], v[136:137], v[138:139]
	v_pk_add_f32 v[98:99], v[112:113], v[98:99]
	v_pk_mul_f32 v[112:113], v[86:87], v[86:87]
	v_pk_add_f32 v[98:99], v[136:137], v[98:99]
	v_pk_mul_f32 v[136:137], v[84:85], v[84:85]
	v_pk_add_f32 v[98:99], v[98:99], v[98:99] op_sel_hi:[0,1]
	v_pk_mov_b32 v[138:139], v[136:137], v[112:113] op_sel:[1,0]
	v_mov_b32_e32 v137, v113
	v_mul_f32_e32 v98, v88, v88
	v_pk_add_f32 v[112:113], v[138:139], v[136:137]
	v_pk_fma_f32 v[136:137], v[88:89], v[88:89], v[98:99] op_sel_hi:[1,1,0]
	v_mul_f32_e32 v98, v90, v90
	v_pk_add_f32 v[112:113], v[112:113], v[112:113] op_sel_hi:[0,1]
	v_pk_fma_f32 v[138:139], v[90:91], v[90:91], v[98:99] op_sel_hi:[1,1,0]
	v_mul_f32_e32 v136, v92, v92
	v_mul_f32_e32 v138, v93, v93
	v_mul_f32_e32 v112, v94, v94
	v_mul_f32_e32 v98, v95, v95
	v_pk_add_f32 v[136:137], v[136:137], v[138:139]
	v_pk_add_f32 v[98:99], v[112:113], v[98:99]
	v_ashrrev_i32_e32 v96, 12, v96
	v_pk_add_f32 v[98:99], v[136:137], v[98:99]
	v_mul_hi_i32_i24_e32 v97, 0xc000, v96
	v_add_f32_e32 v98, v98, v99
	v_mul_i32_i24_e32 v96, 0xc000, v96
	v_lshlrev_b32_e32 v184, 2, v196
	s_waitcnt lgkmcnt(0)
	s_nop 1
	v_add_f32_dpp v98, v98, v98 quad_perm:[1,0,3,2] row_mask:0xf bank_mask:0xf
	s_waitcnt lgkmcnt(0)
	s_nop 1
	v_add_f32_dpp v98, v98, v98 quad_perm:[2,3,0,1] row_mask:0xf bank_mask:0xf
	s_waitcnt lgkmcnt(0)
	s_nop 1
	v_add_f32_dpp v98, v98, v98 row_half_mirror row_mask:0xf bank_mask:0xf
	s_waitcnt lgkmcnt(0)
	s_nop 1
	v_add_f32_dpp v98, v98, v98 row_mirror row_mask:0xf bank_mask:0xf
	s_waitcnt lgkmcnt(0)
	v_mov_b32_e32 v99, v98
	s_nop 1
	v_permlane16_swap_b32_e32 v98, v99
	v_add_f32_e32 v98, v98, v99
	s_waitcnt lgkmcnt(0)
; DI void ew2(ArgsRef a, int l) {
;     ...
;         const float r1 = row_rms_scale(y);
;         ld_row_f32(t, a.in[I_GPOSTFFN] + l * DM, lane);
; #pragma unroll
;         for (int i = 0; i < 8; ++i) y.v[i] = y.v[i] * r1 * t.v[i];
;         ld_row_f32(t, md + 5 * DM, lane);
; #pragma unroll
;         for (int i = 0; i < 8; ++i) x.v[i] = x.v[i] + t.v[i] * y.v[i];
;         if (l == 0) st_row_bf16(x, (bf16_t*)xo, lane); else st_row_f32(x, xo, lane);
	v_mov_b32_e32 v99, v98
	s_nop 1
	v_permlane32_swap_b32_e32 v98, v99
	v_add_f32_e32 v98, v98, v99
	v_fmamk_f32 v98, v98, 0x3a000000, v189
	v_cmp_gt_f32_e32 vcc, s71, v98
	v_mul_f32_e32 v99, 0x4f800000, v98
	s_nop 0
	v_cndmask_b32_e32 v98, v98, v99, vcc
	v_sqrt_f32_e32 v99, v98
	s_nop 0
	v_add_u32_e32 v112, -1, v99
	v_fma_f32 v113, -v112, v99, v98
	v_cmp_ge_f32_e64 s[10:11], 0, v113
	v_add_u32_e32 v113, 1, v99
	s_nop 0
	v_cndmask_b32_e64 v112, v99, v112, s[10:11]
	v_fma_f32 v99, -v113, v99, v98
	v_cmp_lt_f32_e64 s[10:11], 0, v99
	s_nop 1
	v_cndmask_b32_e64 v99, v112, v113, s[10:11]
	v_mul_f32_e32 v112, 0x37800000, v99
	v_cndmask_b32_e32 v99, v99, v112, vcc
	v_cmp_class_f32_e32 vcc, v98, v227
	s_nop 1
	v_cndmask_b32_e32 v98, v99, v98, vcc
	v_div_scale_f32 v99, s[10:11], v98, v98, 1.0
	v_rcp_f32_e32 v112, v99
	s_mov_b64 s[10:11], 0xb000
	v_fma_f32 v113, -v99, v112, 1.0
	v_fmac_f32_e32 v112, v113, v112
	v_div_scale_f32 v113, vcc, 1.0, v98, 1.0
	v_mul_f32_e32 v136, v113, v112
	v_fma_f32 v137, -v99, v136, v113
	v_fmac_f32_e32 v136, v137, v112
	v_fma_f32 v99, -v99, v136, v113
	v_div_fmas_f32 v99, v99, v112, v136
	global_load_dwordx4 v[136:139], v[202:203], off offset:16
	global_load_dwordx4 v[140:143], v[202:203], off
	global_load_dwordx4 v[144:147], v[202:203], off offset:2064
	global_load_dwordx4 v[148:151], v[202:203], off offset:2048
	global_load_dwordx4 v[170:173], v[204:205], off offset:16
	global_load_dwordx4 v[174:177], v[204:205], off
	global_load_dwordx4 v[178:181], v[206:207], off offset:16
	global_load_dwordx4 v[234:237], v[206:207], off
	v_div_fixup_f32 v98, v99, v98, 1.0
	v_pk_mul_f32 v[64:65], v[64:65], v[98:99] op_sel_hi:[1,0]
	v_pk_mul_f32 v[66:67], v[66:67], v[98:99] op_sel_hi:[1,0]
	v_lshl_add_u64 v[112:113], s[78:79], 0, v[96:97]
	s_waitcnt vmcnt(6)
	v_pk_mul_f32 v[164:165], v[140:141], v[64:65]
	v_pk_mul_f32 v[64:65], v[70:71], v[98:99] op_sel_hi:[1,0]
	v_pk_mul_f32 v[166:167], v[142:143], v[66:67]
	v_pk_mul_f32 v[162:163], v[138:139], v[64:65]
	v_pk_mul_f32 v[64:65], v[74:75], v[98:99] op_sel_hi:[1,0]
	v_pk_mul_f32 v[66:67], v[68:69], v[98:99] op_sel_hi:[1,0]
	s_waitcnt vmcnt(4)
	v_pk_mul_f32 v[158:159], v[150:151], v[64:65]
	v_pk_mul_f32 v[64:65], v[78:79], v[98:99] op_sel_hi:[1,0]
	v_pk_mul_f32 v[160:161], v[136:137], v[66:67]
	v_pk_mul_f32 v[66:67], v[72:73], v[98:99] op_sel_hi:[1,0]
	v_pk_mul_f32 v[154:155], v[146:147], v[64:65]
	v_pk_mul_f32 v[64:65], v[82:83], v[98:99] op_sel_hi:[1,0]
	v_pk_mul_f32 v[156:157], v[148:149], v[66:67]
	v_pk_mul_f32 v[66:67], v[76:77], v[98:99] op_sel_hi:[1,0]
	s_waitcnt vmcnt(2)
	v_pk_mul_f32 v[150:151], v[176:177], v[64:65]
	v_pk_mul_f32 v[64:65], v[86:87], v[98:99] op_sel_hi:[1,0]
	v_pk_mul_f32 v[152:153], v[144:145], v[66:67]
	v_pk_mul_f32 v[66:67], v[80:81], v[98:99] op_sel_hi:[1,0]
	v_pk_mul_f32 v[146:147], v[172:173], v[64:65]
	v_pk_mul_f32 v[64:65], v[90:91], v[98:99] op_sel_hi:[1,0]
	v_pk_mul_f32 v[148:149], v[174:175], v[66:67]
	v_pk_mul_f32 v[66:67], v[84:85], v[98:99] op_sel_hi:[1,0]
	s_waitcnt vmcnt(0)
	v_pk_mul_f32 v[142:143], v[236:237], v[64:65]
	v_pk_mul_f32 v[64:65], v[94:95], v[98:99] op_sel_hi:[1,0]
	v_pk_mul_f32 v[144:145], v[170:171], v[66:67]
	v_pk_mul_f32 v[66:67], v[88:89], v[98:99] op_sel_hi:[1,0]
	v_pk_mul_f32 v[138:139], v[180:181], v[64:65]
	v_lshl_add_u64 v[64:65], v[112:113], 0, v[184:185]
	v_pk_mul_f32 v[140:141], v[234:235], v[66:67]
	v_pk_mul_f32 v[66:67], v[92:93], v[98:99] op_sel_hi:[1,0]
	v_add_co_u32_e32 v92, vcc, s51, v64
	v_pk_mul_f32 v[136:137], v[178:179], v[66:67]
	v_lshl_add_u64 v[66:67], v[64:65], 0, s[36:37]
	v_addc_co_u32_e32 v93, vcc, 0, v65, vcc
	global_load_dwordx4 v[88:91], v[92:93], off offset:-4096
	global_load_dwordx4 v[84:87], v[66:67], off offset:16
	global_load_dwordx4 v[68:71], v[66:67], off offset:2064
	global_load_dwordx4 v[80:83], v[66:67], off offset:2048
	v_lshl_add_u64 v[66:67], v[64:65], 0, s[10:11]
	v_lshl_add_u64 v[64:65], v[64:65], 0, s[38:39]
	global_load_dwordx4 v[76:79], v[92:93], off
	global_load_dwordx4 v[72:75], v[66:67], off offset:16
	global_load_dwordx4 v[96:99], v[92:93], off offset:2048
	s_nop 0
	global_load_dwordx4 v[64:67], v[64:65], off offset:16
	s_mov_b64 s[10:11], -1
	s_and_b64 vcc, exec, s[60:61]
	s_waitcnt vmcnt(7)
	v_pk_fma_f32 v[94:95], v[90:91], v[166:167], v[134:135]
	v_pk_fma_f32 v[92:93], v[88:89], v[164:165], v[132:133]
	s_waitcnt vmcnt(6)
	v_pk_fma_f32 v[90:91], v[162:163], v[86:87], v[130:131]
	v_pk_fma_f32 v[88:89], v[160:161], v[84:85], v[128:129]
	s_waitcnt vmcnt(4)
	v_pk_fma_f32 v[86:87], v[158:159], v[82:83], v[126:127]
	v_pk_fma_f32 v[84:85], v[156:157], v[80:81], v[124:125]
	v_pk_fma_f32 v[82:83], v[154:155], v[70:71], v[122:123]
	v_pk_fma_f32 v[80:81], v[152:153], v[68:69], v[120:121]
	s_waitcnt vmcnt(3)
	v_pk_fma_f32 v[78:79], v[150:151], v[78:79], v[118:119]
	v_pk_fma_f32 v[76:77], v[148:149], v[76:77], v[116:117]
	s_waitcnt vmcnt(2)
	v_pk_fma_f32 v[74:75], v[146:147], v[74:75], v[114:115]
	v_pk_fma_f32 v[72:73], v[144:145], v[72:73], v[110:111]
	s_waitcnt vmcnt(1)
	v_pk_fma_f32 v[70:71], v[142:143], v[98:99], v[108:109]
	v_pk_fma_f32 v[68:69], v[140:141], v[96:97], v[106:107]
	s_waitcnt vmcnt(0)
	v_pk_fma_f32 v[66:67], v[138:139], v[66:67], v[104:105]
	v_pk_fma_f32 v[64:65], v[136:137], v[64:65], v[102:103]
	s_cbranch_vccz .LBB0_463
	v_lshl_add_u64 v[96:97], v[100:101], 0, v[184:185]
	global_store_dwordx4 v[96:97], v[92:95], off
	global_store_dwordx4 v[96:97], v[88:91], off offset:16
	global_store_dwordx4 v[96:97], v[84:87], off offset:2048
	global_store_dwordx4 v[96:97], v[80:83], off offset:2064
	v_add_co_u32_e32 v96, vcc, 0x1000, v96
	s_mov_b64 s[10:11], 0
	s_nop 0
	v_addc_co_u32_e32 v97, vcc, 0, v97, vcc
	global_store_dwordx4 v[96:97], v[76:79], off
	global_store_dwordx4 v[96:97], v[72:75], off offset:16
	global_store_dwordx4 v[96:97], v[68:71], off offset:2048
	global_store_dwordx4 v[96:97], v[64:67], off offset:2064

; DI float row_rms_scale(const Row32& r) {
;     float s = 0.f;
; #pragma unroll
;     for (int i = 0; i < 8; ++i) s += (r.v[i].x * r.v[i].x + r.v[i].y * r.v[i].y) + (r.v[i].z * r.v[i].z + r.v[i].w * r.v[i].w);
;     s = wave_sum(s);
;     return 1.0f / sqrtf(s * (1.f / DM) + EPS);
; }
; DI void norm_mod_store(const Row32& x, float rs, const float* g, const float* shift, const float* scale, bf16_t* dst, int lane) {
;     Row32 gg, sh, sc, o; ld_row_f32(gg, g, lane); ld_row_f32(sh, shift, lane); ld_row_f32(sc, scale, lane);
; #pragma unroll
;     for (int i = 0; i < 8; ++i) o.v[i] = (x.v[i] * rs * gg.v[i]) * (1.f + sc.v[i]) + sh.v[i];
;     st_row_bf16(o, dst, lane);
; }
; DI void ew2(ArgsRef a, int l) {
;     ...
;         if (l == 0) st_row_bf16(x, (bf16_t*)xo, lane); else st_row_f32(x, xo, lane);
;         if (l == 0) {
;             const float r2 = row_rms_scale(x);
;             const float* md1 = md + (size_t)9 * NMODS;
;             norm_mod_store(x, r2, a.in[I_GPREMIX] + DM, md1 + 0 * DM, md1 + 1 * DM, H + hpad_row(g) * DM, lane);
.LBB0_465:
	v_readlane_b32 s12, v254, 36
	v_readlane_b32 s13, v254, 37
	s_andn2_b64 vcc, exec, s[12:13]
	s_nop 0
	v_cndmask_b32_e64 v96, 0, 1, s[12:13]
	v_cmp_ne_u32_e64 s[10:11], 1, v96
	s_cbranch_vccnz .LBB0_471
	v_mul_f32_e32 v96, v93, v93
	v_mul_f32_e32 v97, v95, v95
	v_fmac_f32_e32 v96, v92, v92
	v_fmac_f32_e32 v97, v94, v94
	v_add_f32_e32 v96, v96, v97
	v_mul_f32_e32 v97, v89, v89
	v_mul_f32_e32 v98, v91, v91
	v_fmac_f32_e32 v97, v88, v88
	v_fmac_f32_e32 v98, v90, v90
	v_add_f32_e32 v97, v97, v98
	v_add_f32_e32 v96, v96, v97
	v_mul_f32_e32 v97, v85, v85
	v_mul_f32_e32 v98, v87, v87
	v_fmac_f32_e32 v97, v84, v84
	v_fmac_f32_e32 v98, v86, v86
	v_add_f32_e32 v97, v97, v98
	v_add_f32_e32 v96, v96, v97
	v_mul_f32_e32 v97, v81, v81
	v_mul_f32_e32 v98, v83, v83
	v_fmac_f32_e32 v97, v80, v80
	v_fmac_f32_e32 v98, v82, v82
	v_add_f32_e32 v97, v97, v98
	v_add_f32_e32 v96, v96, v97
	v_mul_f32_e32 v97, v77, v77
	v_mul_f32_e32 v98, v79, v79
	v_fmac_f32_e32 v97, v76, v76
	v_fmac_f32_e32 v98, v78, v78
	v_add_f32_e32 v97, v97, v98
	v_add_f32_e32 v96, v96, v97
	v_mul_f32_e32 v97, v73, v73
	v_mul_f32_e32 v98, v75, v75
	v_fmac_f32_e32 v97, v72, v72
	v_fmac_f32_e32 v98, v74, v74
	v_add_f32_e32 v97, v97, v98
	v_add_f32_e32 v96, v96, v97
	v_mul_f32_e32 v97, v69, v69
	v_mul_f32_e32 v98, v71, v71
	v_fmac_f32_e32 v97, v68, v68
	v_fmac_f32_e32 v98, v70, v70
	v_add_f32_e32 v97, v97, v98
	v_add_f32_e32 v96, v96, v97
	v_mul_f32_e32 v97, v65, v65
	v_mul_f32_e32 v98, v67, v67
	v_fmac_f32_e32 v97, v64, v64
	v_fmac_f32_e32 v98, v66, v66
	v_add_f32_e32 v97, v97, v98
	v_add_f32_e32 v96, v96, v97
	s_waitcnt lgkmcnt(0)
	s_nop 1
	v_add_f32_dpp v96, v96, v96 quad_perm:[1,0,3,2] row_mask:0xf bank_mask:0xf
	s_waitcnt lgkmcnt(0)
	s_nop 1
	v_add_f32_dpp v96, v96, v96 quad_perm:[2,3,0,1] row_mask:0xf bank_mask:0xf
	s_waitcnt lgkmcnt(0)
	s_nop 1
	v_add_f32_dpp v96, v96, v96 row_half_mirror row_mask:0xf bank_mask:0xf
	s_waitcnt lgkmcnt(0)
	s_nop 1
	v_add_f32_dpp v96, v96, v96 row_mirror row_mask:0xf bank_mask:0xf
	s_waitcnt lgkmcnt(0)
	v_mov_b32_e32 v97, v96
	s_nop 1
	v_permlane16_swap_b32_e32 v96, v97
	v_add_f32_e32 v99, v96, v97
	ds_bpermute_b32 v100, v246, v99
	s_and_saveexec_b64 s[12:13], s[8:9]
	s_xor_b64 s[8:9], exec, s[12:13]
	v_lshrrev_b32_e32 v96, 8, v168
	v_mul_hi_u32_u24_e32 v97, 0x102, v96
	v_mul_u32_u24_e32 v96, 0x102, v96
	s_or_saveexec_b64 s[8:9], s[8:9]
	v_mov_b32_e32 v98, 0x8011
	v_mov_b32_e32 v101, 0xff
	s_xor_b64 exec, exec, s[8:9]
	v_ashrrev_i32_e32 v96, 12, v194
	v_mul_hi_i32_i24_e32 v97, 0x1002, v96
	v_mul_i32_i24_e32 v96, 0x1002, v96
	v_mov_b32_e32 v98, 1
	v_mov_b32_e32 v101, 0xfff
	s_or_b64 exec, exec, s[8:9]
	s_waitcnt lgkmcnt(0)
	v_add_f32_e32 v99, v99, v100
	v_fmamk_f32 v99, v99, 0x3a000000, v189
	v_cmp_gt_f32_e32 vcc, s71, v99
	v_mul_f32_e32 v100, 0x4f800000, v99
	v_lshl_add_u64 v[234:235], v[112:113], 0, v[184:185]
	v_cndmask_b32_e32 v99, v99, v100, vcc
	v_sqrt_f32_e32 v100, v99
	v_lshl_add_u64 v[112:113], v[234:235], 0, s[40:41]
	v_lshl_add_u64 v[168:169], v[234:235], 0, s[54:55]
	v_lshl_add_u64 v[172:173], v[234:235], 0, s[56:57]
	v_add_u32_e32 v102, -1, v100
	v_fma_f32 v103, -v102, v100, v99
	v_cmp_ge_f32_e64 s[8:9], 0, v103
	v_add_u32_e32 v103, 1, v100
	v_lshl_add_u64 v[248:249], v[234:235], 0, s[58:59]
	v_cndmask_b32_e64 v102, v100, v102, s[8:9]
	v_fma_f32 v100, -v103, v100, v99
	v_cmp_lt_f32_e64 s[8:9], 0, v100
	s_nop 1
	v_cndmask_b32_e64 v100, v102, v103, s[8:9]
	v_mul_f32_e32 v102, 0x37800000, v100
	v_cndmask_b32_e32 v100, v100, v102, vcc
	v_cmp_class_f32_e32 vcc, v99, v227
	s_nop 1
	v_cndmask_b32_e32 v99, v100, v99, vcc
	v_div_scale_f32 v100, s[8:9], v99, v99, 1.0
	v_rcp_f32_e32 v102, v100
	s_mov_b32 s8, 0x6d000
	v_fma_f32 v103, -v100, v102, 1.0
	v_fmac_f32_e32 v102, v103, v102
	v_div_scale_f32 v103, vcc, 1.0, v99, 1.0
	v_mul_f32_e32 v104, v103, v102
	v_fma_f32 v105, -v100, v104, v103
	v_fmac_f32_e32 v104, v105, v102
	v_fma_f32 v100, -v100, v104, v103
	v_div_fmas_f32 v100, v100, v102, v104
	v_div_fixup_f32 v226, v100, v99, 1.0
	v_and_b32_e32 v99, v101, v194
	v_add_u32_e32 v98, v99, v98
	v_mov_b32_e32 v99, v185
	v_add_co_u32_e32 v114, vcc, s8, v234
	v_lshl_add_u64 v[96:97], v[96:97], 0, v[98:99]
	s_nop 0
	v_addc_co_u32_e32 v115, vcc, 0, v235, vcc
	s_mov_b32 s8, 0x6f000
	v_lshlrev_b64 v[224:225], 12, v[96:97]
	global_load_dwordx4 v[96:99], v[208:209], off offset:16
	global_load_dwordx4 v[148:151], v[208:209], off
	global_load_dwordx4 v[124:127], v[208:209], off offset:2064
	global_load_dwordx4 v[132:135], v[208:209], off offset:2048
	global_load_dwordx4 v[108:111], v[210:211], off offset:16
	global_load_dwordx4 v[116:119], v[210:211], off
	global_load_dwordx4 v[100:103], v[212:213], off offset:16
	global_load_dwordx4 v[104:107], v[212:213], off
	global_load_dwordx4 v[156:159], v[114:115], off offset:-4096
	global_load_dwordx4 v[152:155], v[112:113], off offset:16
	global_load_dwordx4 v[140:143], v[112:113], off offset:2064
	global_load_dwordx4 v[144:147], v[112:113], off offset:2048
	v_lshl_add_u64 v[112:113], v[234:235], 0, s[44:45]
	v_add_co_u32_e32 v236, vcc, s8, v234
	global_load_dwordx4 v[136:139], v[114:115], off
	global_load_dwordx4 v[128:131], v[112:113], off offset:16
	v_lshl_add_u64 v[112:113], v[234:235], 0, s[46:47]
	v_addc_co_u32_e32 v237, vcc, 0, v235, vcc
	global_load_dwordx4 v[120:123], v[114:115], off offset:2048
	s_nop 0
	global_load_dwordx4 v[112:115], v[112:113], off offset:16
	s_nop 0
	global_load_dwordx4 v[176:179], v[236:237], off offset:-4096
	global_load_dwordx4 v[164:167], v[168:169], off offset:16
	global_load_dwordx4 v[160:163], v[168:169], off offset:2064
	s_nop 0
	global_load_dwordx4 v[168:171], v[168:169], off offset:2048
	s_nop 0
	global_load_dwordx4 v[180:183], v[236:237], off
	s_nop 0
	global_load_dwordx4 v[172:175], v[172:173], off offset:16
	s_nop 0
	global_load_dwordx4 v[234:237], v[236:237], off offset:2048
	s_nop 0
	global_load_dwordx4 v[248:251], v[248:249], off offset:16
	v_pk_mul_f32 v[90:91], v[90:91], v[226:227] op_sel_hi:[1,0]
	v_pk_mul_f32 v[88:89], v[88:89], v[226:227] op_sel_hi:[1,0]
	v_pk_mul_f32 v[86:87], v[86:87], v[226:227] op_sel_hi:[1,0]
	v_pk_mul_f32 v[84:85], v[84:85], v[226:227] op_sel_hi:[1,0]
	v_pk_mul_f32 v[82:83], v[82:83], v[226:227] op_sel_hi:[1,0]
	v_pk_mul_f32 v[80:81], v[80:81], v[226:227] op_sel_hi:[1,0]
	v_pk_mul_f32 v[78:79], v[78:79], v[226:227] op_sel_hi:[1,0]
	v_pk_mul_f32 v[76:77], v[76:77], v[226:227] op_sel_hi:[1,0]
	v_pk_mul_f32 v[74:75], v[74:75], v[226:227] op_sel_hi:[1,0]
	v_pk_mul_f32 v[72:73], v[72:73], v[226:227] op_sel_hi:[1,0]
	v_pk_mul_f32 v[94:95], v[94:95], v[226:227] op_sel_hi:[1,0]
	v_pk_mul_f32 v[92:93], v[92:93], v[226:227] op_sel_hi:[1,0]
	v_pk_mul_f32 v[70:71], v[70:71], v[226:227] op_sel_hi:[1,0]
	v_pk_mul_f32 v[68:69], v[68:69], v[226:227] op_sel_hi:[1,0]
	v_pk_mul_f32 v[66:67], v[66:67], v[226:227] op_sel_hi:[1,0]
	v_pk_mul_f32 v[64:65], v[64:65], v[226:227] op_sel_hi:[1,0]
	s_waitcnt vmcnt(23)
; DI void norm_mod_store(const Row32& x, float rs, const float* g, const float* shift, const float* scale, bf16_t* dst, int lane) {
;     Row32 gg, sh, sc, o; ld_row_f32(gg, g, lane); ld_row_f32(sh, shift, lane); ld_row_f32(sc, scale, lane);
; #pragma unroll
;     for (int i = 0; i < 8; ++i) o.v[i] = (x.v[i] * rs * gg.v[i]) * (1.f + sc.v[i]) + sh.v[i];
;     st_row_bf16(o, dst, lane);
; }
; DI void ew2(ArgsRef a, int l) {
;     ...
;             norm_mod_store(x, r2, a.in[I_GPREMIX] + DM, md1 + 0 * DM, md1 + 1 * DM, H + hpad_row(g) * DM, lane);
;         } };
;     for (int g = gw; g < nrows; g += 2 * NGW) {
;         const int g2 = g + NGW; const bool has2 = g2 < nrows;
;         Row32 yA, xA, yB, xB;
;         load(g, yA, xA);
;         if (has2) load(g2, yB, xB);
;         finish(g, yA, xA);
	v_pk_mul_f32 v[88:89], v[88:89], v[96:97]
	v_pk_mul_f32 v[90:91], v[90:91], v[98:99]
	s_waitcnt vmcnt(21)
	v_pk_mul_f32 v[80:81], v[80:81], v[124:125]
	s_waitcnt vmcnt(20)
	v_pk_mul_f32 v[84:85], v[84:85], v[132:133]
	v_pk_mul_f32 v[86:87], v[86:87], v[134:135]
	v_pk_mul_f32 v[82:83], v[82:83], v[126:127]
	s_waitcnt vmcnt(18)
	v_pk_mul_f32 v[76:77], v[76:77], v[116:117]
	v_pk_mul_f32 v[78:79], v[78:79], v[118:119]
	v_pk_mul_f32 v[72:73], v[72:73], v[108:109]
	v_pk_mul_f32 v[74:75], v[74:75], v[110:111]
	v_pk_mul_f32 v[92:93], v[92:93], v[148:149]
	v_pk_mul_f32 v[94:95], v[94:95], v[150:151]
	s_waitcnt vmcnt(16)
	v_pk_mul_f32 v[68:69], v[68:69], v[104:105]
	v_pk_mul_f32 v[70:71], v[70:71], v[106:107]
	s_waitcnt vmcnt(7)
	v_pk_add_f32 v[148:149], v[178:179], 1.0 op_sel_hi:[1,0]
	s_waitcnt vmcnt(6)
	v_pk_add_f32 v[96:97], v[166:167], 1.0 op_sel_hi:[1,0]
	v_pk_add_f32 v[98:99], v[164:165], 1.0 op_sel_hi:[1,0]
	v_pk_fma_f32 v[90:91], v[90:91], v[96:97], v[154:155]
	v_pk_fma_f32 v[88:89], v[88:89], v[98:99], v[152:153]
	s_waitcnt vmcnt(4)
	v_pk_add_f32 v[96:97], v[170:171], 1.0 op_sel_hi:[1,0]
	v_pk_add_f32 v[98:99], v[168:169], 1.0 op_sel_hi:[1,0]
	v_pk_fma_f32 v[86:87], v[86:87], v[96:97], v[146:147]
	v_pk_fma_f32 v[84:85], v[84:85], v[98:99], v[144:145]
	v_pk_add_f32 v[96:97], v[162:163], 1.0 op_sel_hi:[1,0]
	v_pk_add_f32 v[98:99], v[160:161], 1.0 op_sel_hi:[1,0]
	v_pk_fma_f32 v[82:83], v[82:83], v[96:97], v[142:143]
	v_pk_fma_f32 v[80:81], v[80:81], v[98:99], v[140:141]
	s_waitcnt vmcnt(3)
	v_pk_add_f32 v[96:97], v[182:183], 1.0 op_sel_hi:[1,0]
	v_pk_add_f32 v[98:99], v[180:181], 1.0 op_sel_hi:[1,0]
	v_pk_fma_f32 v[78:79], v[78:79], v[96:97], v[138:139]
	v_pk_fma_f32 v[76:77], v[76:77], v[98:99], v[136:137]
	s_waitcnt vmcnt(2)
	v_pk_add_f32 v[96:97], v[174:175], 1.0 op_sel_hi:[1,0]
	v_pk_add_f32 v[98:99], v[172:173], 1.0 op_sel_hi:[1,0]
	v_pk_add_f32 v[150:151], v[176:177], 1.0 op_sel_hi:[1,0]
	v_pk_fma_f32 v[74:75], v[74:75], v[96:97], v[130:131]
	v_pk_fma_f32 v[72:73], v[72:73], v[98:99], v[128:129]
	s_waitcnt vmcnt(1)
	v_pk_add_f32 v[96:97], v[236:237], 1.0 op_sel_hi:[1,0]
	v_pk_add_f32 v[98:99], v[234:235], 1.0 op_sel_hi:[1,0]
	v_pk_fma_f32 v[94:95], v[94:95], v[148:149], v[158:159]
	v_pk_fma_f32 v[92:93], v[92:93], v[150:151], v[156:157]
	v_pk_fma_f32 v[70:71], v[70:71], v[96:97], v[122:123]
	v_pk_fma_f32 v[68:69], v[68:69], v[98:99], v[120:121]
	v_pk_mul_f32 v[64:65], v[64:65], v[100:101]
	v_pk_mul_f32 v[66:67], v[66:67], v[102:103]
	s_waitcnt vmcnt(0)
	v_pk_add_f32 v[96:97], v[250:251], 1.0 op_sel_hi:[1,0]
	v_pk_add_f32 v[98:99], v[248:249], 1.0 op_sel_hi:[1,0]
	v_pk_fma_f32 v[96:97], v[66:67], v[96:97], v[114:115]
	v_pk_fma_f32 v[98:99], v[64:65], v[98:99], v[112:113]
	v_lshl_add_u64 v[100:101], v[214:215], 0, v[224:225]
	v_cvt_pk_bf16_f32 v64, v92, v93
	v_cvt_pk_bf16_f32 v65, v94, v95
	v_cvt_pk_bf16_f32 v66, v88, v89
	v_cvt_pk_bf16_f32 v67, v90, v91
	global_store_dwordx4 v[100:101], v[64:67], off
	s_nop 1
	v_cvt_pk_bf16_f32 v64, v84, v85
	v_cvt_pk_bf16_f32 v65, v86, v87
	v_cvt_pk_bf16_f32 v66, v80, v81
	v_cvt_pk_bf16_f32 v67, v82, v83
	global_store_dwordx4 v[100:101], v[64:67], off offset:1024
	s_nop 1
	v_cvt_pk_bf16_f32 v64, v76, v77
	v_cvt_pk_bf16_f32 v65, v78, v79
	v_cvt_pk_bf16_f32 v66, v72, v73
	v_cvt_pk_bf16_f32 v67, v74, v75
	global_store_dwordx4 v[100:101], v[64:67], off offset:2048
	s_nop 1
	v_cvt_pk_bf16_f32 v64, v68, v69
	v_cvt_pk_bf16_f32 v65, v70, v71
	v_cvt_pk_bf16_f32 v66, v98, v99
	v_cvt_pk_bf16_f32 v67, v96, v97
	global_store_dwordx4 v[100:101], v[64:67], off offset:3072
.LBB0_471:
	s_and_saveexec_b64 s[12:13], s[6:7]
	s_cbranch_execz .LBB0_450
	v_cmp_gt_i32_e32 vcc, s87, v220
	v_add_u32_e32 v100, 0xffff8000, v220
	v_ashrrev_i32_e32 v64, 31, v220
	v_mov_b32_e32 v66, s97
	v_mov_b32_e32 v67, s15
	v_cndmask_b32_e32 v65, 0, v64, vcc
	v_cndmask_b32_e32 v64, v100, v220, vcc
	v_cndmask_b32_e32 v67, v66, v67, vcc
	v_mov_b32_e32 v66, s96
	v_mov_b32_e32 v68, s14
	v_cndmask_b32_e32 v66, v66, v68, vcc
	v_lshlrev_b64 v[64:65], 13, v[64:65]
	v_mov_b32_e32 v68, v5
	v_mov_b32_e32 v69, v1
	v_lshl_add_u64 v[96:97], v[66:67], 0, v[64:65]
	v_mov_b32_e32 v66, v4
	v_mov_b32_e32 v67, v0
	v_pk_mul_f32 v[68:69], v[68:69], v[68:69]
	v_mov_b32_e32 v70, v7
	v_mov_b32_e32 v71, v3
	v_pk_fma_f32 v[66:67], v[66:67], v[66:67], v[68:69]
	v_mov_b32_e32 v68, v6
	v_mov_b32_e32 v69, v2
	v_pk_mul_f32 v[70:71], v[70:71], v[70:71]
	v_min_i32_e32 v64, 0x8000, v220
	v_pk_fma_f32 v[68:69], v[68:69], v[68:69], v[70:71]
	v_pk_mul_f32 v[70:71], v[8:9], v[8:9]
	v_pk_add_f32 v[66:67], v[66:67], v[68:69]
	v_pk_mul_f32 v[68:69], v[10:11], v[10:11]
	v_pk_add_f32 v[66:67], v[66:67], v[66:67] op_sel_hi:[0,1]
	v_pk_mov_b32 v[72:73], v[70:71], v[68:69] op_sel:[1,0]
	v_mov_b32_e32 v71, v69
	v_mul_f32_e32 v66, v12, v12
	v_pk_add_f32 v[68:69], v[72:73], v[70:71]
	v_pk_fma_f32 v[70:71], v[12:13], v[12:13], v[66:67] op_sel_hi:[1,1,0]
	v_mul_f32_e32 v66, v14, v14
	v_pk_add_f32 v[68:69], v[68:69], v[68:69] op_sel_hi:[0,1]
	v_pk_fma_f32 v[72:73], v[14:15], v[14:15], v[66:67] op_sel_hi:[1,1,0]
	v_mul_f32_e32 v70, v16, v16
	v_mul_f32_e32 v72, v17, v17
	v_mul_f32_e32 v68, v18, v18
	v_mul_f32_e32 v66, v19, v19
	v_pk_add_f32 v[70:71], v[70:71], v[72:73]
	v_pk_add_f32 v[66:67], v[68:69], v[66:67]
	v_pk_mul_f32 v[68:69], v[22:23], v[22:23]
	v_pk_add_f32 v[66:67], v[70:71], v[66:67]
	v_pk_mul_f32 v[70:71], v[20:21], v[20:21]
	v_pk_add_f32 v[66:67], v[66:67], v[66:67] op_sel_hi:[0,1]
	v_pk_mov_b32 v[72:73], v[70:71], v[68:69] op_sel:[1,0]
	v_mov_b32_e32 v71, v69
	v_mul_f32_e32 v66, v24, v24
	v_pk_add_f32 v[68:69], v[72:73], v[70:71]
	v_pk_fma_f32 v[70:71], v[24:25], v[24:25], v[66:67] op_sel_hi:[1,1,0]
	v_mul_f32_e32 v66, v26, v26
	v_pk_add_f32 v[68:69], v[68:69], v[68:69] op_sel_hi:[0,1]
	v_pk_fma_f32 v[72:73], v[26:27], v[26:27], v[66:67] op_sel_hi:[1,1,0]
	v_mul_f32_e32 v70, v28, v28
	v_mul_f32_e32 v72, v29, v29
	v_mul_f32_e32 v68, v30, v30
	v_mul_f32_e32 v66, v31, v31
	v_pk_add_f32 v[70:71], v[70:71], v[72:73]
	v_pk_add_f32 v[66:67], v[68:69], v[66:67]
	v_ashrrev_i32_e32 v64, 12, v64
	v_pk_add_f32 v[66:67], v[70:71], v[66:67]
	v_mul_hi_i32_i24_e32 v65, 0xc000, v64
	v_add_f32_e32 v66, v66, v67
	v_mul_i32_i24_e32 v64, 0xc000, v64
	v_lshl_add_u64 v[98:99], s[78:79], 0, v[64:65]
	v_cmp_lt_i32_e64 s[6:7], s63, v220
	s_waitcnt lgkmcnt(0)
; DI void ew2(ArgsRef a, int l) {
;     ...
;         const float r1 = row_rms_scale(y);
;         ld_row_f32(t, a.in[I_GPOSTFFN] + l * DM, lane);
; #pragma unroll
;         for (int i = 0; i < 8; ++i) y.v[i] = y.v[i] * r1 * t.v[i];
;         ld_row_f32(t, md + 5 * DM, lane);
; #pragma unroll
;         for (int i = 0; i < 8; ++i) x.v[i] = x.v[i] + t.v[i] * y.v[i];
;         if (l == 0) st_row_bf16(x, (bf16_t*)xo, lane); else st_row_f32(x, xo, lane);
	s_nop 1
	v_add_f32_dpp v66, v66, v66 quad_perm:[1,0,3,2] row_mask:0xf bank_mask:0xf
	s_waitcnt lgkmcnt(0)
	s_nop 1
	v_add_f32_dpp v66, v66, v66 quad_perm:[2,3,0,1] row_mask:0xf bank_mask:0xf
	s_waitcnt lgkmcnt(0)
	s_nop 1
	v_add_f32_dpp v66, v66, v66 row_half_mirror row_mask:0xf bank_mask:0xf
	s_waitcnt lgkmcnt(0)
	s_nop 1
	v_add_f32_dpp v66, v66, v66 row_mirror row_mask:0xf bank_mask:0xf
	s_waitcnt lgkmcnt(0)
	v_mov_b32_e32 v67, v66
	s_nop 1
	v_permlane16_swap_b32_e32 v66, v67
	v_add_f32_e32 v66, v66, v67
	s_waitcnt lgkmcnt(0)
	v_mov_b32_e32 v67, v66
	s_nop 1
	v_permlane32_swap_b32_e32 v66, v67
	v_add_f32_e32 v66, v66, v67
	v_fmamk_f32 v66, v66, 0x3a000000, v189
	v_cmp_gt_f32_e32 vcc, s71, v66
	v_mul_f32_e32 v67, 0x4f800000, v66
	s_nop 0
	v_cndmask_b32_e32 v66, v66, v67, vcc
	v_sqrt_f32_e32 v67, v66
	s_nop 0
	v_add_u32_e32 v68, -1, v67
	v_fma_f32 v69, -v68, v67, v66
	v_cmp_ge_f32_e64 s[8:9], 0, v69
	v_add_u32_e32 v69, 1, v67
	s_nop 0
	v_cndmask_b32_e64 v68, v67, v68, s[8:9]
	v_fma_f32 v67, -v69, v67, v66
	v_cmp_lt_f32_e64 s[8:9], 0, v67
	s_nop 1
	v_cndmask_b32_e64 v67, v68, v69, s[8:9]
	v_mul_f32_e32 v68, 0x37800000, v67
	v_cndmask_b32_e32 v67, v67, v68, vcc
	v_cmp_class_f32_e32 vcc, v66, v227
	s_nop 1
	v_cndmask_b32_e32 v66, v67, v66, vcc
	v_div_scale_f32 v67, s[8:9], v66, v66, 1.0
	v_rcp_f32_e32 v68, v67
	s_mov_b64 s[8:9], 0xb000
	v_fma_f32 v69, -v67, v68, 1.0
	v_fmac_f32_e32 v68, v69, v68
	v_div_scale_f32 v69, vcc, 1.0, v66, 1.0
	v_mul_f32_e32 v70, v69, v68
	v_fma_f32 v71, -v67, v70, v69
	v_fmac_f32_e32 v70, v71, v68
	v_fma_f32 v67, -v67, v70, v69
	v_div_fmas_f32 v67, v67, v68, v70
	global_load_dwordx4 v[68:71], v[202:203], off offset:16
	global_load_dwordx4 v[72:75], v[202:203], off
	global_load_dwordx4 v[76:79], v[202:203], off offset:2064
	global_load_dwordx4 v[80:83], v[202:203], off offset:2048
	global_load_dwordx4 v[84:87], v[204:205], off offset:16
	global_load_dwordx4 v[88:91], v[204:205], off
	global_load_dwordx4 v[92:95], v[206:207], off offset:16
	global_load_dwordx4 v[102:105], v[206:207], off
	v_div_fixup_f32 v66, v67, v66, 1.0
	v_pk_mul_f32 v[4:5], v[66:67], v[4:5] op_sel_hi:[0,1]
	v_pk_mul_f32 v[12:13], v[66:67], v[12:13] op_sel_hi:[0,1]
	v_pk_mul_f32 v[6:7], v[66:67], v[6:7] op_sel_hi:[0,1]
	v_pk_mul_f32 v[16:17], v[66:67], v[16:17] op_sel_hi:[0,1]
	v_pk_mul_f32 v[18:19], v[66:67], v[18:19] op_sel_hi:[0,1]
	v_pk_mul_f32 v[20:21], v[66:67], v[20:21] op_sel_hi:[0,1]
	v_pk_mul_f32 v[22:23], v[66:67], v[22:23] op_sel_hi:[0,1]
	v_pk_mul_f32 v[28:29], v[66:67], v[28:29] op_sel_hi:[0,1]
	v_pk_mul_f32 v[30:31], v[66:67], v[30:31] op_sel_hi:[0,1]
	v_pk_mul_f32 v[0:1], v[66:67], v[0:1] op_sel_hi:[0,1]
	v_pk_mul_f32 v[2:3], v[66:67], v[2:3] op_sel_hi:[0,1]
	v_pk_mul_f32 v[8:9], v[66:67], v[8:9] op_sel_hi:[0,1]
	v_pk_mul_f32 v[10:11], v[66:67], v[10:11] op_sel_hi:[0,1]
	v_pk_mul_f32 v[14:15], v[66:67], v[14:15] op_sel_hi:[0,1]
	v_pk_mul_f32 v[24:25], v[66:67], v[24:25] op_sel_hi:[0,1]
	v_pk_mul_f32 v[26:27], v[66:67], v[26:27] op_sel_hi:[0,1]
	s_waitcnt vmcnt(7)
	v_pk_mul_f32 v[4:5], v[68:69], v[4:5]
	v_lshl_add_u64 v[68:69], v[98:99], 0, v[184:185]
	s_waitcnt vmcnt(5)
	v_pk_mul_f32 v[12:13], v[76:77], v[12:13]
	v_add_co_u32_e32 v76, vcc, s51, v68
	v_pk_mul_f32 v[6:7], v[70:71], v[6:7]
	v_lshl_add_u64 v[70:71], v[68:69], 0, s[36:37]
	v_addc_co_u32_e32 v77, vcc, 0, v69, vcc
	s_waitcnt vmcnt(2)
	v_pk_mul_f32 v[18:19], v[90:91], v[18:19]
	v_pk_mul_f32 v[16:17], v[88:89], v[16:17]
	v_pk_mul_f32 v[22:23], v[86:87], v[22:23]
	v_pk_mul_f32 v[20:21], v[84:85], v[20:21]
	s_waitcnt vmcnt(1)
	v_pk_mul_f32 v[30:31], v[94:95], v[30:31]
	v_pk_mul_f32 v[28:29], v[92:93], v[28:29]
	global_load_dwordx4 v[92:95], v[76:77], off offset:-4096
	global_load_dwordx4 v[84:87], v[70:71], off offset:16
	global_load_dwordx4 v[64:67], v[70:71], off offset:2064
	global_load_dwordx4 v[88:91], v[70:71], off offset:2048
	v_lshl_add_u64 v[70:71], v[68:69], 0, s[8:9]
	v_lshl_add_u64 v[68:69], v[68:69], 0, s[38:39]
	v_pk_mul_f32 v[2:3], v[74:75], v[2:3]
	v_pk_mul_f32 v[0:1], v[72:73], v[0:1]
	v_pk_mul_f32 v[10:11], v[82:83], v[10:11]
	v_pk_mul_f32 v[8:9], v[80:81], v[8:9]
	v_pk_mul_f32 v[14:15], v[78:79], v[14:15]
	global_load_dwordx4 v[80:83], v[76:77], off
	global_load_dwordx4 v[72:75], v[70:71], off offset:16
	s_nop 0
	global_load_dwordx4 v[76:79], v[76:77], off offset:2048
	s_nop 0
	global_load_dwordx4 v[68:71], v[68:69], off offset:16
	s_waitcnt vmcnt(8)
	v_pk_mul_f32 v[26:27], v[104:105], v[26:27]
	v_pk_mul_f32 v[24:25], v[102:103], v[24:25]
	s_mov_b64 s[8:9], -1
	s_and_b64 vcc, exec, s[60:61]
	s_waitcnt vmcnt(7)
	v_pk_fma_f32 v[34:35], v[94:95], v[2:3], v[34:35]
	v_pk_fma_f32 v[32:33], v[92:93], v[0:1], v[32:33]
	s_waitcnt vmcnt(6)
	v_pk_fma_f32 v[38:39], v[86:87], v[6:7], v[38:39]
	v_pk_fma_f32 v[36:37], v[84:85], v[4:5], v[36:37]
	s_waitcnt vmcnt(4)
	v_pk_fma_f32 v[42:43], v[10:11], v[90:91], v[42:43]
	v_pk_fma_f32 v[40:41], v[8:9], v[88:89], v[40:41]
	v_pk_fma_f32 v[46:47], v[14:15], v[66:67], v[46:47]
	v_pk_fma_f32 v[44:45], v[12:13], v[64:65], v[44:45]
	s_waitcnt vmcnt(3)
	v_pk_fma_f32 v[50:51], v[18:19], v[82:83], v[50:51]
	v_pk_fma_f32 v[48:49], v[16:17], v[80:81], v[48:49]
	s_waitcnt vmcnt(2)
	v_pk_fma_f32 v[54:55], v[22:23], v[74:75], v[54:55]
	v_pk_fma_f32 v[52:53], v[20:21], v[72:73], v[52:53]
	s_waitcnt vmcnt(1)
	v_pk_fma_f32 v[58:59], v[26:27], v[78:79], v[58:59]
	v_pk_fma_f32 v[56:57], v[24:25], v[76:77], v[56:57]
	s_waitcnt vmcnt(0)
	v_pk_fma_f32 v[62:63], v[30:31], v[70:71], v[62:63]
	v_pk_fma_f32 v[60:61], v[28:29], v[68:69], v[60:61]
	s_cbranch_vccz .LBB0_475
	v_lshl_add_u64 v[64:65], v[96:97], 0, v[184:185]
	global_store_dwordx4 v[64:65], v[32:35], off
	global_store_dwordx4 v[64:65], v[36:39], off offset:16
	global_store_dwordx4 v[64:65], v[40:43], off offset:2048
	global_store_dwordx4 v[64:65], v[44:47], off offset:2064
	v_add_co_u32_e32 v64, vcc, 0x1000, v64
	s_nop 1
	v_addc_co_u32_e32 v65, vcc, 0, v65, vcc
	global_store_dwordx4 v[64:65], v[48:51], off
	global_store_dwordx4 v[64:65], v[52:55], off offset:16
	global_store_dwordx4 v[64:65], v[56:59], off offset:2048
	global_store_dwordx4 v[64:65], v[60:63], off offset:2064
	s_cbranch_execz .LBB0_476

; DI void ew2(ArgsRef a, int l) {
;     ...
;         if (l == 0) st_row_bf16(x, (bf16_t*)xo, lane); else st_row_f32(x, xo, lane);
;         if (l == 0) {
;             const float r2 = row_rms_scale(x);
;             const float* md1 = md + (size_t)9 * NMODS;
;             norm_mod_store(x, r2, a.in[I_GPREMIX] + DM, md1 + 0 * DM, md1 + 1 * DM, H + hpad_row(g) * DM, lane);
.LBB0_477:
	v_mul_f32_e32 v64, v33, v33
	v_mul_f32_e32 v65, v35, v35
	v_fmac_f32_e32 v64, v32, v32
	v_fmac_f32_e32 v65, v34, v34
	v_add_f32_e32 v64, v64, v65
	v_mul_f32_e32 v65, v37, v37
	v_mul_f32_e32 v66, v39, v39
	v_fmac_f32_e32 v65, v36, v36
	v_fmac_f32_e32 v66, v38, v38
	v_add_f32_e32 v65, v65, v66
	v_add_f32_e32 v64, v64, v65
	v_mul_f32_e32 v65, v41, v41
	v_mul_f32_e32 v66, v43, v43
	v_fmac_f32_e32 v65, v40, v40
	v_fmac_f32_e32 v66, v42, v42
	v_add_f32_e32 v65, v65, v66
	v_add_f32_e32 v64, v64, v65
	v_mul_f32_e32 v65, v45, v45
	v_mul_f32_e32 v66, v47, v47
	v_fmac_f32_e32 v65, v44, v44
	v_fmac_f32_e32 v66, v46, v46
	v_add_f32_e32 v65, v65, v66
	v_add_f32_e32 v64, v64, v65
	v_mul_f32_e32 v65, v49, v49
	v_mul_f32_e32 v66, v51, v51
	v_fmac_f32_e32 v65, v48, v48
	v_fmac_f32_e32 v66, v50, v50
	v_add_f32_e32 v65, v65, v66
	v_add_f32_e32 v64, v64, v65
	v_mul_f32_e32 v65, v53, v53
	v_mul_f32_e32 v66, v55, v55
	v_fmac_f32_e32 v65, v52, v52
	v_fmac_f32_e32 v66, v54, v54
	v_add_f32_e32 v65, v65, v66
	v_add_f32_e32 v64, v64, v65
	v_mul_f32_e32 v65, v57, v57
	v_mul_f32_e32 v66, v59, v59
	v_fmac_f32_e32 v65, v56, v56
	v_fmac_f32_e32 v66, v58, v58
	v_add_f32_e32 v65, v65, v66
	v_add_f32_e32 v64, v64, v65
	v_mul_f32_e32 v65, v61, v61
	v_mul_f32_e32 v66, v63, v63
	v_fmac_f32_e32 v65, v60, v60
	v_fmac_f32_e32 v66, v62, v62
	v_add_f32_e32 v65, v65, v66
	v_add_f32_e32 v64, v64, v65
	s_waitcnt lgkmcnt(0)
	s_nop 1
	v_add_f32_dpp v64, v64, v64 quad_perm:[1,0,3,2] row_mask:0xf bank_mask:0xf
	s_waitcnt lgkmcnt(0)
	s_nop 1
	v_add_f32_dpp v64, v64, v64 quad_perm:[2,3,0,1] row_mask:0xf bank_mask:0xf
	s_waitcnt lgkmcnt(0)
	s_nop 1
	v_add_f32_dpp v64, v64, v64 row_half_mirror row_mask:0xf bank_mask:0xf
	s_waitcnt lgkmcnt(0)
	s_nop 1
	v_add_f32_dpp v64, v64, v64 row_mirror row_mask:0xf bank_mask:0xf
	s_waitcnt lgkmcnt(0)
	v_mov_b32_e32 v65, v64
	s_nop 1
	v_permlane16_swap_b32_e32 v64, v65
	v_add_f32_e32 v66, v64, v65
	ds_bpermute_b32 v67, v246, v66
	s_and_saveexec_b64 s[8:9], s[6:7]
	s_xor_b64 s[6:7], exec, s[8:9]
	v_lshrrev_b32_e32 v64, 8, v100
	v_mul_hi_u32_u24_e32 v65, 0x102, v64
	v_mul_u32_u24_e32 v64, 0x102, v64
	s_or_saveexec_b64 s[6:7], s[6:7]
	v_mov_b32_e32 v68, 0x8011
	v_mov_b32_e32 v69, 0xff
	s_xor_b64 exec, exec, s[6:7]
	s_cbranch_execz .LBB0_449
	v_ashrrev_i32_e32 v64, 12, v220
	v_mul_hi_i32_i24_e32 v65, 0x1002, v64
	v_mul_i32_i24_e32 v64, 0x1002, v64
	v_mov_b32_e32 v68, 1
	v_mov_b32_e32 v69, 0xfff
	s_branch .LBB0_449

; DI void p0_mods_item(LAS unsigned char* lds, ArgsRef a, float* MODS, int item) {
;     ...
; #pragma unroll 4
;     for (int k = ks * 128; k < ks * 128 + 128; ++k) {
;         const f32x4 w = *(const f32x4*)(W + (size_t)k * NMODS);
; #pragma unroll
;         for (int b = 0; b < 9; ++b) acc[b] += sc[k * 9 + b] * w;
;     }
.LBB0_754:
	v_lshl_add_u64 v[40:41], v[38:39], 0, s[6:7]
	global_load_dwordx4 v[46:49], v[40:41], off
	v_add_co_u32_e32 v88, vcc, s42, v40
	s_nop 1
	v_addc_co_u32_e32 v89, vcc, 0, v41, vcc
	global_load_dwordx4 v[76:79], v[88:89], off
	v_add_co_u32_e32 v90, vcc, 0x18000, v40
	s_nop 1
	v_addc_co_u32_e32 v91, vcc, 0, v41, vcc
	global_load_dwordx4 v[80:83], v[90:91], off
	v_add_co_u32_e32 v92, vcc, 0x24000, v40
	s_nop 1
	v_addc_co_u32_e32 v93, vcc, 0, v41, vcc
	global_load_dwordx4 v[84:87], v[92:93], off
	ds_read_b128 v[50:53], v44
	ds_read_b128 v[54:57], v44 offset:16
	ds_read_b128 v[58:61], v44 offset:32
	ds_read_b128 v[62:65], v44 offset:48
	s_add_u32 s6, s6, 0x30000
	s_addc_u32 s7, s7, 0
	s_cmp_eq_u32 s6, 0x600000
	s_waitcnt vmcnt(3) lgkmcnt(3)
	v_pk_fma_f32 v[2:3], v[48:49], v[50:51], v[2:3] op_sel_hi:[1,0,1]
	v_pk_fma_f32 v[0:1], v[46:47], v[50:51], v[0:1] op_sel_hi:[1,0,1]
	v_pk_fma_f32 v[18:19], v[48:49], v[50:51], v[18:19] op_sel:[0,1,0]
	v_pk_fma_f32 v[16:17], v[46:47], v[50:51], v[16:17] op_sel:[0,1,0]
	v_pk_fma_f32 v[12:13], v[46:47], v[52:53], v[12:13] op_sel_hi:[1,0,1]
	v_pk_fma_f32 v[14:15], v[48:49], v[52:53], v[14:15] op_sel_hi:[1,0,1]
	v_mov_b32_e32 v50, v53
	s_waitcnt lgkmcnt(2)
	v_pk_fma_f32 v[52:53], v[46:47], v[54:55], v[4:5] op_sel_hi:[1,0,1]
	v_mov_b32_e32 v4, v57
	v_pk_fma_f32 v[8:9], v[46:47], v[50:51], v[8:9] op_sel_hi:[1,0,1]
	v_pk_fma_f32 v[10:11], v[48:49], v[50:51], v[10:11] op_sel_hi:[1,0,1]
	v_pk_fma_f32 v[50:51], v[48:49], v[54:55], v[6:7] op_sel_hi:[1,0,1]
	v_pk_fma_f32 v[34:35], v[48:49], v[54:55], v[34:35] op_sel:[0,1,0]
	v_pk_fma_f32 v[32:33], v[46:47], v[54:55], v[32:33] op_sel:[0,1,0]
	v_pk_fma_f32 v[54:55], v[46:47], v[56:57], v[28:29] op_sel_hi:[1,0,1]
	v_pk_fma_f32 v[30:31], v[48:49], v[56:57], v[30:31] op_sel_hi:[1,0,1]
	v_pk_fma_f32 v[24:25], v[46:47], v[4:5], v[24:25] op_sel_hi:[1,0,1]
	v_pk_fma_f32 v[56:57], v[48:49], v[4:5], v[26:27] op_sel_hi:[1,0,1]
	s_waitcnt lgkmcnt(1)
	v_pk_fma_f32 v[46:47], v[46:47], v[58:59], v[20:21] op_sel_hi:[1,0,1]
	v_pk_fma_f32 v[48:49], v[48:49], v[58:59], v[22:23] op_sel_hi:[1,0,1]
	s_waitcnt vmcnt(2)
	v_pk_fma_f32 v[66:67], v[76:77], v[58:59], v[0:1] op_sel:[0,1,0]
	v_mov_b32_e32 v0, v61
	s_waitcnt lgkmcnt(0)
	v_pk_fma_f32 v[20:21], v[78:79], v[62:63], v[10:11] op_sel_hi:[1,0,1]
	v_mov_b32_e32 v10, v65
	v_pk_fma_f32 v[68:69], v[76:77], v[60:61], v[16:17] op_sel_hi:[1,0,1]
	v_pk_fma_f32 v[70:71], v[78:79], v[60:61], v[18:19] op_sel_hi:[1,0,1]
	v_pk_fma_f32 v[4:5], v[76:77], v[0:1], v[12:13] op_sel_hi:[1,0,1]
	v_pk_fma_f32 v[18:19], v[78:79], v[0:1], v[14:15] op_sel_hi:[1,0,1]
	v_pk_fma_f32 v[0:1], v[76:77], v[64:65], v[32:33] op_sel_hi:[1,0,1]
	v_pk_fma_f32 v[16:17], v[78:79], v[10:11], v[30:31] op_sel_hi:[1,0,1]
	ds_read_b128 v[30:33], v44 offset:64
	v_pk_fma_f32 v[58:59], v[78:79], v[58:59], v[2:3] op_sel:[0,1,0]
	v_pk_fma_f32 v[6:7], v[76:77], v[62:63], v[8:9] op_sel_hi:[1,0,1]
	v_pk_fma_f32 v[8:9], v[76:77], v[62:63], v[52:53] op_sel:[0,1,0]
	v_pk_fma_f32 v[22:23], v[78:79], v[62:63], v[50:51] op_sel:[0,1,0]
	v_pk_fma_f32 v[14:15], v[78:79], v[64:65], v[34:35] op_sel_hi:[1,0,1]
	v_pk_fma_f32 v[2:3], v[76:77], v[10:11], v[54:55] op_sel_hi:[1,0,1]
	s_waitcnt lgkmcnt(0)
	v_pk_fma_f32 v[10:11], v[76:77], v[30:31], v[24:25] op_sel_hi:[1,0,1]
	v_pk_fma_f32 v[24:25], v[78:79], v[30:31], v[56:57] op_sel_hi:[1,0,1]
	v_pk_fma_f32 v[12:13], v[76:77], v[30:31], v[46:47] op_sel:[0,1,0]
	v_pk_fma_f32 v[26:27], v[78:79], v[30:31], v[48:49] op_sel:[0,1,0]
	s_waitcnt vmcnt(1)
	v_pk_fma_f32 v[46:47], v[82:83], v[32:33], v[58:59] op_sel_hi:[1,0,1]
	v_pk_fma_f32 v[48:49], v[80:81], v[32:33], v[66:67] op_sel_hi:[1,0,1]
	v_mov_b32_e32 v32, v33
	v_pk_fma_f32 v[50:51], v[82:83], v[32:33], v[70:71] op_sel_hi:[1,0,1]
	v_pk_fma_f32 v[52:53], v[80:81], v[32:33], v[68:69] op_sel_hi:[1,0,1]
	ds_read_b128 v[32:35], v44 offset:80
	s_waitcnt lgkmcnt(0)
	v_pk_fma_f32 v[56:57], v[80:81], v[32:33], v[4:5] op_sel_hi:[1,0,1]
	v_mov_b32_e32 v4, v35
	v_pk_fma_f32 v[64:65], v[80:81], v[4:5], v[0:1] op_sel_hi:[1,0,1]
	v_pk_fma_f32 v[58:59], v[82:83], v[32:33], v[20:21] op_sel:[0,1,0]
	v_pk_fma_f32 v[60:61], v[82:83], v[34:35], v[22:23] op_sel_hi:[1,0,1]
	v_pk_fma_f32 v[54:55], v[82:83], v[32:33], v[18:19] op_sel_hi:[1,0,1]
	v_pk_fma_f32 v[32:33], v[80:81], v[32:33], v[6:7] op_sel:[0,1,0]
	v_pk_fma_f32 v[62:63], v[80:81], v[34:35], v[8:9] op_sel_hi:[1,0,1]
	v_pk_fma_f32 v[34:35], v[82:83], v[4:5], v[14:15] op_sel_hi:[1,0,1]
	ds_read_b128 v[4:7], v44 offset:96
	s_waitcnt lgkmcnt(0)
	v_mov_b32_e32 v0, v7
	v_pk_fma_f32 v[66:67], v[82:83], v[4:5], v[16:17] op_sel_hi:[1,0,1]
	v_pk_fma_f32 v[68:69], v[80:81], v[4:5], v[2:3] op_sel_hi:[1,0,1]
	v_pk_fma_f32 v[24:25], v[82:83], v[4:5], v[24:25] op_sel:[0,1,0]
	v_pk_fma_f32 v[70:71], v[80:81], v[4:5], v[10:11] op_sel:[0,1,0]
	v_pk_fma_f32 v[72:73], v[82:83], v[6:7], v[26:27] op_sel_hi:[1,0,1]
	v_pk_fma_f32 v[74:75], v[80:81], v[6:7], v[12:13] op_sel_hi:[1,0,1]
	ds_read_b128 v[4:7], v44 offset:112
	s_waitcnt vmcnt(0)
	v_pk_fma_f32 v[2:3], v[86:87], v[0:1], v[46:47] op_sel_hi:[1,0,1]
	v_pk_fma_f32 v[0:1], v[84:85], v[0:1], v[48:49] op_sel_hi:[1,0,1]
	ds_read_b128 v[46:49], v44 offset:128
	s_waitcnt lgkmcnt(1)
	v_pk_fma_f32 v[18:19], v[86:87], v[4:5], v[50:51] op_sel_hi:[1,0,1]
	v_pk_fma_f32 v[16:17], v[84:85], v[4:5], v[52:53] op_sel_hi:[1,0,1]
	v_pk_fma_f32 v[14:15], v[86:87], v[4:5], v[54:55] op_sel:[0,1,0]
	v_pk_fma_f32 v[12:13], v[84:85], v[4:5], v[56:57] op_sel:[0,1,0]
	v_mov_b32_e32 v4, v7
	s_waitcnt lgkmcnt(0)
	v_mov_b32_e32 v40, v49
	v_pk_fma_f32 v[10:11], v[86:87], v[6:7], v[58:59] op_sel_hi:[1,0,1]
	v_pk_fma_f32 v[8:9], v[84:85], v[6:7], v[32:33] op_sel_hi:[1,0,1]
	v_pk_fma_f32 v[6:7], v[86:87], v[4:5], v[60:61] op_sel_hi:[1,0,1]
	v_pk_fma_f32 v[4:5], v[84:85], v[4:5], v[62:63] op_sel_hi:[1,0,1]
	v_pk_fma_f32 v[34:35], v[86:87], v[46:47], v[34:35] op_sel_hi:[1,0,1]
	v_pk_fma_f32 v[32:33], v[84:85], v[46:47], v[64:65] op_sel_hi:[1,0,1]
	v_pk_fma_f32 v[30:31], v[86:87], v[46:47], v[66:67] op_sel:[0,1,0]
	v_pk_fma_f32 v[28:29], v[84:85], v[46:47], v[68:69] op_sel:[0,1,0]
	v_pk_fma_f32 v[26:27], v[86:87], v[48:49], v[24:25] op_sel_hi:[1,0,1]
	v_pk_fma_f32 v[24:25], v[84:85], v[48:49], v[70:71] op_sel_hi:[1,0,1]
	v_pk_fma_f32 v[22:23], v[86:87], v[40:41], v[72:73] op_sel_hi:[1,0,1]
	v_pk_fma_f32 v[20:21], v[84:85], v[40:41], v[74:75] op_sel_hi:[1,0,1]
	v_add_u32_e32 v44, 0x90, v44
	s_cbranch_scc0 .LBB0_754
; #define LAS __attribute__((address_space(3)))
; DI void p0_mods_item(LAS unsigned char* lds, ArgsRef a, float* MODS, int item) {
;     ...
;     __syncthreads();
;     LAS float* red = (LAS float*)lds;
; #pragma unroll
;     for (int b = 0; b < 9; ++b) *(LAS f32x4*)(red + (ks * 9 + b) * 128 + cgp * 4) = acc[b];
;     __syncthreads();
;     for (int o = tid; o < 9 * 128; o += 512) { const int b = o >> 7, cc = o & 127; float s = 0.f;
; #pragma unroll
;         for (int k2 = 0; k2 < 16; ++k2) s += red[(k2 * 9 + b) * 128 + cc];
;         MODS[(size_t)(l * 9 + b) * NMODS + chunk * 128 + cc] = s + a.in[I_BADA][l * NMODS + chunk * 128 + cc]; }
	v_lshlrev_b32_e32 v38, 2, v42
	s_movk_i32 s6, 0x480
	v_add3_u32 v38, 0, v38, v43
	v_cmp_gt_i32_e32 vcc, s6, v37
	s_barrier
	ds_write_b128 v38, v[0:3]
	ds_write_b128 v38, v[16:19] offset:512
	ds_write_b128 v38, v[12:15] offset:1024
	ds_write_b128 v38, v[8:11] offset:1536
	ds_write_b128 v38, v[4:7] offset:2048
	ds_write_b128 v38, v[32:35] offset:2560
	ds_write_b128 v38, v[28:31] offset:3072
	ds_write_b128 v38, v[24:27] offset:3584
	ds_write_b128 v38, v[20:23] offset:4096
	s_waitcnt lgkmcnt(0)
	s_barrier
	s_and_saveexec_b64 s[6:7], vcc
	s_cbranch_execz .LBB0_746
	s_mul_i32 s16, s12, 0xffffffa0
	s_add_i32 s16, s16, s15
	s_lshl_b32 s18, s16, 7
	s_ashr_i32 s19, s18, 31
	s_add_i32 s17, s18, s13
	s_mul_i32 s16, s12, 9
	s_lshl_b64 s[12:13], s[18:19], 2
	s_load_dwordx2 s[18:19], s[84:85], 0x28
	v_and_b32_e32 v0, 0x7f, v37
	s_add_u32 s12, s82, s12
	v_lshlrev_b32_e32 v184, 2, v0
	v_or_b32_e32 v0, s17, v0
	s_addc_u32 s13, s83, s13
	v_ashrrev_i32_e32 v1, 31, v0
	v_add_u32_e32 v4, 0, v184
	s_waitcnt lgkmcnt(0)
	v_lshl_add_u64 v[0:1], v[0:1], 2, s[18:19]
	v_lshl_add_u64 v[2:3], s[12:13], 0, v[184:185]
	s_mov_b64 s[12:13], 0
